# gemm_mfma_same_accumulator_pairs_remeasure
# speedup vs baseline: 1.0068x; 1.0068x over previous
.LBB0_468:
	s_ashr_i32 s37, s36, 31
	s_lshl_b64 s[40:41], s[36:37], 19
	s_add_u32 s40, s82, s40
	s_addc_u32 s41, s83, s41
	s_and_b64 s[42:43], s[10:11], exec
	s_cselect_b32 s5, s41, s9
	s_cselect_b32 s7, s40, s8
	s_ashr_i32 s39, s38, 31
	s_lshl_b64 s[42:43], s[38:39], 19
	s_add_u32 s42, s12, s42
	s_addc_u32 s43, s13, s43
	s_and_b64 s[44:45], s[10:11], exec
	s_cselect_b32 s37, s43, s3
	s_cselect_b32 s39, s42, s2
	s_add_u32 s8, s8, 0x40080
	s_addc_u32 s9, s9, 0
	s_add_u32 s33, s2, 0x100
	s_addc_u32 s61, s3, 0
	s_mov_b32 s62, -2
	s_add_u32 s2, s8, 0xfffc0080
	s_addc_u32 s3, s9, -1
	s_add_i32 s63, 0, 0x10000
	s_cmp_eq_u32 s62, 12
	s_cselect_b32 s45, s5, s3
	s_cselect_b32 s44, s7, s2
	s_cselect_b32 s3, s37, s61
	s_cselect_b32 s2, s39, s33
	s_add_i32 s66, 0, 0x14000
	v_add_u32_e32 v70, s63, v211
	v_add_u32_e32 v142, s66, v211
	ds_read_b128 v[50:53], v70
	ds_read_b128 v[54:57], v70 offset:1024
	ds_read_b128 v[66:69], v70 offset:2048
	ds_read_b128 v[70:73], v70 offset:3072
	ds_read_b128 v[90:93], v142
	ds_read_b128 v[110:113], v142 offset:1024
	ds_read_b128 v[126:129], v142 offset:2048
	ds_read_b128 v[142:145], v142 offset:3072
	v_lshl_add_u64 v[214:215], s[8:9], 0, v[172:173]
	s_add_i32 m0, s50, 0xc000
	ds_read_b128 v[176:179], v213
	ds_read_b128 v[180:183], v213 offset:1024
	ds_read_b128 v[186:189], v213 offset:2048
	ds_read_b128 v[190:193], v213 offset:3072
	ds_read_b128 v[194:197], v213 offset:4096
	ds_read_b128 v[198:201], v213 offset:5120
	ds_read_b128 v[202:205], v213 offset:6144
	ds_read_b128 v[206:209], v213 offset:7168
	global_load_lds_dwordx4 v[214:215], off
	v_lshl_add_u64 v[214:215], s[8:9], 0, v[174:175]
	s_add_i32 m0, s50, 0xe000
	s_nop 0
	global_load_lds_dwordx4 v[214:215], off
	s_waitcnt vmcnt(8)
	s_waitcnt lgkmcnt(0)
	s_barrier
	s_setprio 1
	s_waitcnt lgkmcnt(0)
	v_mfma_f32_16x16x32_bf16 v[158:161], v[50:53], v[176:179], 0
	v_mfma_f32_16x16x32_bf16 v[158:161], v[54:57], v[180:183], v[158:161]
	v_mfma_f32_16x16x32_bf16 v[154:157], v[66:69], v[176:179], 0
	v_mfma_f32_16x16x32_bf16 v[154:157], v[70:73], v[180:183], v[154:157]
	v_mfma_f32_16x16x32_bf16 v[138:141], v[50:53], v[186:189], 0
	v_mfma_f32_16x16x32_bf16 v[138:141], v[54:57], v[190:193], v[138:141]
	v_mfma_f32_16x16x32_bf16 v[134:137], v[66:69], v[186:189], 0
	v_mfma_f32_16x16x32_bf16 v[134:137], v[70:73], v[190:193], v[134:137]
	v_mfma_f32_16x16x32_bf16 v[118:121], v[50:53], v[194:197], 0
	v_mfma_f32_16x16x32_bf16 v[118:121], v[54:57], v[198:201], v[118:121]
	v_mfma_f32_16x16x32_bf16 v[114:117], v[66:69], v[194:197], 0
	v_mfma_f32_16x16x32_bf16 v[114:117], v[70:73], v[198:201], v[114:117]
	v_mfma_f32_16x16x32_bf16 v[98:101], v[50:53], v[202:205], 0
	v_mfma_f32_16x16x32_bf16 v[98:101], v[54:57], v[206:209], v[98:101]
	v_mfma_f32_16x16x32_bf16 v[94:97], v[66:69], v[202:205], 0
	v_mfma_f32_16x16x32_bf16 v[94:97], v[70:73], v[206:209], v[94:97]
	s_setprio 0
	s_setprio 1
	v_mfma_f32_16x16x32_bf16 v[150:153], v[90:93], v[176:179], 0
	v_mfma_f32_16x16x32_bf16 v[150:153], v[110:113], v[180:183], v[150:153]
	v_mfma_f32_16x16x32_bf16 v[146:149], v[126:129], v[176:179], 0
	v_mfma_f32_16x16x32_bf16 v[146:149], v[142:145], v[180:183], v[146:149]
	v_mfma_f32_16x16x32_bf16 v[130:133], v[90:93], v[186:189], 0
	v_mfma_f32_16x16x32_bf16 v[130:133], v[110:113], v[190:193], v[130:133]
	v_mfma_f32_16x16x32_bf16 v[122:125], v[126:129], v[186:189], 0
	v_mfma_f32_16x16x32_bf16 v[122:125], v[142:145], v[190:193], v[122:125]
	v_mfma_f32_16x16x32_bf16 v[106:109], v[90:93], v[194:197], 0
	v_mfma_f32_16x16x32_bf16 v[106:109], v[110:113], v[198:201], v[106:109]
	v_mfma_f32_16x16x32_bf16 v[102:105], v[126:129], v[194:197], 0
	v_mfma_f32_16x16x32_bf16 v[102:105], v[142:145], v[198:201], v[102:105]
	v_mfma_f32_16x16x32_bf16 v[86:89], v[90:93], v[202:205], 0
	v_mfma_f32_16x16x32_bf16 v[86:89], v[110:113], v[206:209], v[86:89]
	v_mfma_f32_16x16x32_bf16 v[82:85], v[126:129], v[202:205], 0
	v_mfma_f32_16x16x32_bf16 v[82:85], v[142:145], v[206:209], v[82:85]
	s_setprio 0
	s_barrier
	s_add_i32 s63, s63, s49
	v_lshl_add_u64 v[214:215], s[2:3], 0, v[0:1]
	s_mov_b32 m0, s63
	ds_read_b128 v[176:179], v213 offset:16384
	ds_read_b128 v[180:183], v213 offset:17408
	ds_read_b128 v[186:189], v213 offset:18432
	ds_read_b128 v[190:193], v213 offset:19456
	ds_read_b128 v[194:197], v213 offset:20480
	ds_read_b128 v[198:201], v213 offset:21504
	ds_read_b128 v[202:205], v213 offset:22528
	ds_read_b128 v[206:209], v213 offset:23552
	global_load_lds_dwordx4 v[214:215], off
	s_add_i32 m0, s63, 0x2000
	s_add_u32 s64, s2, 0x40000
	v_lshl_add_u64 v[216:217], s[2:3], 0, v[166:167]
	s_addc_u32 s65, s3, 0
	s_add_i32 s63, s66, s49
	global_load_lds_dwordx4 v[216:217], off
	v_lshl_add_u64 v[218:219], s[64:65], 0, v[0:1]
	s_mov_b32 m0, s63
	v_lshl_add_u64 v[220:221], s[44:45], 0, v[164:165]
	global_load_lds_dwordx4 v[218:219], off
	v_lshl_add_u64 v[218:219], s[64:65], 0, v[166:167]
	s_add_i32 m0, s63, 0x2000
	s_nop 0
	global_load_lds_dwordx4 v[218:219], off
	v_lshl_add_u64 v[218:219], s[44:45], 0, v[162:163]
	s_mov_b32 m0, s50
	s_nop 0
	global_load_lds_dwordx4 v[218:219], off
	s_mov_b32 m0, s51
	s_nop 0
	global_load_lds_dwordx4 v[220:221], off
	s_waitcnt vmcnt(8)
	s_waitcnt lgkmcnt(0)
	s_barrier
	s_setprio 1
	s_waitcnt lgkmcnt(0)
	v_mfma_f32_16x16x32_bf16 v[78:81], v[50:53], v[176:179], 0
	v_mfma_f32_16x16x32_bf16 v[78:81], v[54:57], v[180:183], v[78:81]
	v_mfma_f32_16x16x32_bf16 v[74:77], v[66:69], v[176:179], 0
	v_mfma_f32_16x16x32_bf16 v[74:77], v[70:73], v[180:183], v[74:77]
	v_mfma_f32_16x16x32_bf16 v[46:49], v[50:53], v[186:189], 0
	v_mfma_f32_16x16x32_bf16 v[46:49], v[54:57], v[190:193], v[46:49]
	v_mfma_f32_16x16x32_bf16 v[42:45], v[66:69], v[186:189], 0
	v_mfma_f32_16x16x32_bf16 v[42:45], v[70:73], v[190:193], v[42:45]
	v_mfma_f32_16x16x32_bf16 v[30:33], v[50:53], v[194:197], 0
	v_mfma_f32_16x16x32_bf16 v[30:33], v[54:57], v[198:201], v[30:33]
	v_mfma_f32_16x16x32_bf16 v[26:29], v[66:69], v[194:197], 0
	v_mfma_f32_16x16x32_bf16 v[26:29], v[70:73], v[198:201], v[26:29]
	v_mfma_f32_16x16x32_bf16 v[14:17], v[50:53], v[202:205], 0
	v_mfma_f32_16x16x32_bf16 v[14:17], v[54:57], v[206:209], v[14:17]
	v_mfma_f32_16x16x32_bf16 v[10:13], v[66:69], v[202:205], 0
	v_mfma_f32_16x16x32_bf16 v[10:13], v[70:73], v[206:209], v[10:13]
	s_setprio 0
	s_setprio 1
	v_mfma_f32_16x16x32_bf16 v[38:41], v[90:93], v[186:189], 0
	v_mfma_f32_16x16x32_bf16 v[38:41], v[110:113], v[190:193], v[38:41]
	v_mfma_f32_16x16x32_bf16 v[34:37], v[126:129], v[186:189], 0
	v_mfma_f32_16x16x32_bf16 v[34:37], v[142:145], v[190:193], v[34:37]
	v_mfma_f32_16x16x32_bf16 v[22:25], v[90:93], v[194:197], 0
	v_mfma_f32_16x16x32_bf16 v[22:25], v[110:113], v[198:201], v[22:25]
	v_mfma_f32_16x16x32_bf16 v[18:21], v[126:129], v[194:197], 0
	v_mfma_f32_16x16x32_bf16 v[18:21], v[142:145], v[198:201], v[18:21]
	v_mfma_f32_16x16x32_bf16 v[6:9], v[90:93], v[202:205], 0
	v_mfma_f32_16x16x32_bf16 v[6:9], v[110:113], v[206:209], v[6:9]
	v_mfma_f32_16x16x32_bf16 v[2:5], v[126:129], v[202:205], 0
	v_mfma_f32_16x16x32_bf16 v[2:5], v[142:145], v[206:209], v[2:5]
	v_mfma_f32_16x16x32_bf16 v[50:53], v[90:93], v[176:179], 0
	v_mfma_f32_16x16x32_bf16 v[50:53], v[110:113], v[180:183], v[50:53]
	v_mfma_f32_16x16x32_bf16 v[54:57], v[126:129], v[176:179], 0
	v_mfma_f32_16x16x32_bf16 v[54:57], v[142:145], v[180:183], v[54:57]
	s_setprio 0
	s_barrier
	s_add_i32 s63, 0, 0x18000
	s_add_i32 s64, 0, 0x1c000
	v_add_u32_e32 v70, s63, v211
	v_add_u32_e32 v142, s64, v211
	ds_read_b128 v[58:61], v70
	ds_read_b128 v[62:65], v70 offset:1024
	ds_read_b128 v[66:69], v70 offset:2048
	ds_read_b128 v[70:73], v70 offset:3072
	ds_read_b128 v[90:93], v142
	ds_read_b128 v[110:113], v142 offset:1024
	ds_read_b128 v[126:129], v142 offset:2048
	ds_read_b128 v[142:145], v142 offset:3072
	s_add_u32 s44, s44, 0x40000
	s_addc_u32 s45, s45, 0
	s_mov_b32 m0, s52
	v_lshl_add_u64 v[222:223], s[44:45], 0, v[162:163]
	ds_read_b128 v[176:179], v213 offset:32768
	ds_read_b128 v[180:183], v213 offset:33792
	ds_read_b128 v[186:189], v213 offset:34816
	ds_read_b128 v[190:193], v213 offset:35840
	ds_read_b128 v[194:197], v213 offset:36864
	ds_read_b128 v[198:201], v213 offset:37888
	ds_read_b128 v[202:205], v213 offset:38912
	ds_read_b128 v[206:209], v213 offset:39936
	global_load_lds_dwordx4 v[222:223], off
	v_lshl_add_u64 v[222:223], s[44:45], 0, v[164:165]
	s_mov_b32 m0, s53
	s_nop 0
	global_load_lds_dwordx4 v[222:223], off
	s_waitcnt vmcnt(8)
	s_waitcnt lgkmcnt(0)
	s_barrier
	s_setprio 1
	s_waitcnt lgkmcnt(0)
	v_mfma_f32_16x16x32_bf16 v[158:161], v[58:61], v[176:179], v[158:161]
	v_mfma_f32_16x16x32_bf16 v[158:161], v[62:65], v[180:183], v[158:161]
	v_mfma_f32_16x16x32_bf16 v[154:157], v[66:69], v[176:179], v[154:157]
	v_mfma_f32_16x16x32_bf16 v[154:157], v[70:73], v[180:183], v[154:157]
	v_mfma_f32_16x16x32_bf16 v[138:141], v[58:61], v[186:189], v[138:141]
	v_mfma_f32_16x16x32_bf16 v[138:141], v[62:65], v[190:193], v[138:141]
	v_mfma_f32_16x16x32_bf16 v[134:137], v[66:69], v[186:189], v[134:137]
	v_mfma_f32_16x16x32_bf16 v[134:137], v[70:73], v[190:193], v[134:137]
	v_mfma_f32_16x16x32_bf16 v[118:121], v[58:61], v[194:197], v[118:121]
	v_mfma_f32_16x16x32_bf16 v[118:121], v[62:65], v[198:201], v[118:121]
	v_mfma_f32_16x16x32_bf16 v[114:117], v[66:69], v[194:197], v[114:117]
	v_mfma_f32_16x16x32_bf16 v[114:117], v[70:73], v[198:201], v[114:117]
	v_mfma_f32_16x16x32_bf16 v[98:101], v[58:61], v[202:205], v[98:101]
	v_mfma_f32_16x16x32_bf16 v[98:101], v[62:65], v[206:209], v[98:101]
	v_mfma_f32_16x16x32_bf16 v[94:97], v[66:69], v[202:205], v[94:97]
	v_mfma_f32_16x16x32_bf16 v[94:97], v[70:73], v[206:209], v[94:97]
	s_setprio 0
	s_setprio 1
	v_mfma_f32_16x16x32_bf16 v[150:153], v[90:93], v[176:179], v[150:153]
	v_mfma_f32_16x16x32_bf16 v[150:153], v[110:113], v[180:183], v[150:153]
	v_mfma_f32_16x16x32_bf16 v[146:149], v[126:129], v[176:179], v[146:149]
	v_mfma_f32_16x16x32_bf16 v[146:149], v[142:145], v[180:183], v[146:149]
	v_mfma_f32_16x16x32_bf16 v[130:133], v[90:93], v[186:189], v[130:133]
	v_mfma_f32_16x16x32_bf16 v[130:133], v[110:113], v[190:193], v[130:133]
	v_mfma_f32_16x16x32_bf16 v[122:125], v[126:129], v[186:189], v[122:125]
	v_mfma_f32_16x16x32_bf16 v[122:125], v[142:145], v[190:193], v[122:125]
	v_mfma_f32_16x16x32_bf16 v[106:109], v[90:93], v[194:197], v[106:109]
	v_mfma_f32_16x16x32_bf16 v[106:109], v[110:113], v[198:201], v[106:109]
	v_mfma_f32_16x16x32_bf16 v[102:105], v[126:129], v[194:197], v[102:105]
	v_mfma_f32_16x16x32_bf16 v[102:105], v[142:145], v[198:201], v[102:105]
	v_mfma_f32_16x16x32_bf16 v[86:89], v[90:93], v[202:205], v[86:89]
	v_mfma_f32_16x16x32_bf16 v[86:89], v[110:113], v[206:209], v[86:89]
	v_mfma_f32_16x16x32_bf16 v[82:85], v[126:129], v[202:205], v[82:85]
	v_mfma_f32_16x16x32_bf16 v[82:85], v[142:145], v[206:209], v[82:85]
	s_setprio 0
	s_barrier
	s_add_i32 s44, s63, s49
	v_lshl_add_u64 v[214:215], v[214:215], 0, s[74:75]
	s_mov_b32 m0, s44
	ds_read_b128 v[176:179], v213 offset:49152
	ds_read_b128 v[180:183], v213 offset:50176
	ds_read_b128 v[186:189], v213 offset:51200
	ds_read_b128 v[190:193], v213 offset:52224
	ds_read_b128 v[194:197], v213 offset:53248
	ds_read_b128 v[198:201], v213 offset:54272
	ds_read_b128 v[202:205], v213 offset:55296
	ds_read_b128 v[206:209], v213 offset:56320
	global_load_lds_dwordx4 v[214:215], off
	s_add_i32 m0, s44, 0x2000
	s_add_u32 s2, s2, 0x40080
	v_lshl_add_u64 v[214:215], v[216:217], 0, s[74:75]
	s_addc_u32 s3, s3, 0
	s_add_i32 s44, s64, s49
	global_load_lds_dwordx4 v[214:215], off
	v_lshl_add_u64 v[214:215], s[2:3], 0, v[0:1]
	s_mov_b32 m0, s44
	s_nop 0
	global_load_lds_dwordx4 v[214:215], off
	v_lshl_add_u64 v[214:215], s[2:3], 0, v[166:167]
	s_add_i32 m0, s44, 0x2000
	s_nop 0
	global_load_lds_dwordx4 v[214:215], off
	v_lshl_add_u64 v[214:215], v[218:219], 0, s[74:75]
	s_mov_b32 m0, s55
	s_nop 0
	global_load_lds_dwordx4 v[214:215], off
	v_lshl_add_u64 v[214:215], v[220:221], 0, s[74:75]
	s_mov_b32 m0, s56
	s_nop 0
	global_load_lds_dwordx4 v[214:215], off
	s_waitcnt vmcnt(8)
	s_waitcnt lgkmcnt(0)
	s_barrier
	s_setprio 1
	s_waitcnt lgkmcnt(0)
	v_mfma_f32_16x16x32_bf16 v[78:81], v[58:61], v[176:179], v[78:81]
	v_mfma_f32_16x16x32_bf16 v[78:81], v[62:65], v[180:183], v[78:81]
	v_mfma_f32_16x16x32_bf16 v[74:77], v[66:69], v[176:179], v[74:77]
	v_mfma_f32_16x16x32_bf16 v[74:77], v[70:73], v[180:183], v[74:77]
	v_mfma_f32_16x16x32_bf16 v[46:49], v[58:61], v[186:189], v[46:49]
	v_mfma_f32_16x16x32_bf16 v[46:49], v[62:65], v[190:193], v[46:49]
	v_mfma_f32_16x16x32_bf16 v[42:45], v[66:69], v[186:189], v[42:45]
	v_mfma_f32_16x16x32_bf16 v[42:45], v[70:73], v[190:193], v[42:45]
	v_mfma_f32_16x16x32_bf16 v[30:33], v[58:61], v[194:197], v[30:33]
	v_mfma_f32_16x16x32_bf16 v[30:33], v[62:65], v[198:201], v[30:33]
	v_mfma_f32_16x16x32_bf16 v[26:29], v[66:69], v[194:197], v[26:29]
	v_mfma_f32_16x16x32_bf16 v[26:29], v[70:73], v[198:201], v[26:29]
	v_mfma_f32_16x16x32_bf16 v[14:17], v[58:61], v[202:205], v[14:17]
	v_mfma_f32_16x16x32_bf16 v[14:17], v[62:65], v[206:209], v[14:17]
	v_mfma_f32_16x16x32_bf16 v[10:13], v[66:69], v[202:205], v[10:13]
	v_mfma_f32_16x16x32_bf16 v[10:13], v[70:73], v[206:209], v[10:13]
	s_setprio 0
	s_setprio 1
	v_mfma_f32_16x16x32_bf16 v[50:53], v[90:93], v[176:179], v[50:53]
	v_mfma_f32_16x16x32_bf16 v[62:65], v[110:113], v[180:183], v[50:53]
	v_mfma_f32_16x16x32_bf16 v[50:53], v[126:129], v[176:179], v[54:57]
	v_mfma_f32_16x16x32_bf16 v[38:41], v[90:93], v[186:189], v[38:41]
	v_mfma_f32_16x16x32_bf16 v[34:37], v[126:129], v[186:189], v[34:37]
	v_mfma_f32_16x16x32_bf16 v[22:25], v[90:93], v[194:197], v[22:25]
	v_mfma_f32_16x16x32_bf16 v[18:21], v[126:129], v[194:197], v[18:21]
	v_mfma_f32_16x16x32_bf16 v[6:9], v[90:93], v[202:205], v[6:9]
	v_mfma_f32_16x16x32_bf16 v[2:5], v[126:129], v[202:205], v[2:5]
	v_mfma_f32_16x16x32_bf16 v[58:61], v[142:145], v[180:183], v[50:53]
	v_mfma_f32_16x16x32_bf16 v[38:41], v[110:113], v[190:193], v[38:41]
	v_mfma_f32_16x16x32_bf16 v[34:37], v[142:145], v[190:193], v[34:37]
	v_mfma_f32_16x16x32_bf16 v[22:25], v[110:113], v[198:201], v[22:25]
	v_mfma_f32_16x16x32_bf16 v[18:21], v[142:145], v[198:201], v[18:21]
	v_mfma_f32_16x16x32_bf16 v[6:9], v[110:113], v[206:209], v[6:9]
	v_mfma_f32_16x16x32_bf16 v[2:5], v[142:145], v[206:209], v[2:5]
	s_setprio 0
	s_barrier
	s_add_i32 s62, s62, 2
	s_add_u32 s8, s8, 0x100
	s_addc_u32 s9, s9, 0
	s_add_u32 s33, s33, 0x100
	s_addc_u32 s61, s61, 0
	s_cmp_gt_u32 s62, 13
.LBB0_469:
	s_add_u32 s2, s8, 0xfffc0080
	s_addc_u32 s3, s9, -1
	s_add_i32 s63, 0, 0x10000
	s_cmp_eq_u32 s62, 12
	s_cselect_b32 s45, s5, s3
	s_cselect_b32 s44, s7, s2
	s_cselect_b32 s3, s37, s61
	s_cselect_b32 s2, s39, s33
	s_add_i32 s66, 0, 0x14000
	v_add_u32_e32 v70, s63, v211
	v_add_u32_e32 v142, s66, v211
	ds_read_b128 v[50:53], v70
	ds_read_b128 v[54:57], v70 offset:1024
	ds_read_b128 v[66:69], v70 offset:2048
	ds_read_b128 v[70:73], v70 offset:3072
	ds_read_b128 v[90:93], v142
	ds_read_b128 v[110:113], v142 offset:1024
	ds_read_b128 v[126:129], v142 offset:2048
	ds_read_b128 v[142:145], v142 offset:3072
	v_lshl_add_u64 v[214:215], s[8:9], 0, v[172:173]
	s_add_i32 m0, s50, 0xc000
	ds_read_b128 v[176:179], v213
	ds_read_b128 v[180:183], v213 offset:1024
	ds_read_b128 v[186:189], v213 offset:2048
	ds_read_b128 v[190:193], v213 offset:3072
	ds_read_b128 v[194:197], v213 offset:4096
	ds_read_b128 v[198:201], v213 offset:5120
	ds_read_b128 v[202:205], v213 offset:6144
	ds_read_b128 v[206:209], v213 offset:7168
	global_load_lds_dwordx4 v[214:215], off
	v_lshl_add_u64 v[214:215], s[8:9], 0, v[174:175]
	s_add_i32 m0, s50, 0xe000
	s_nop 0
	global_load_lds_dwordx4 v[214:215], off
	s_waitcnt vmcnt(8)
	s_waitcnt lgkmcnt(0)
	s_barrier
	s_setprio 1
	s_waitcnt lgkmcnt(0)
	v_mfma_f32_16x16x32_bf16 v[158:161], v[50:53], v[176:179], v[158:161]
	v_mfma_f32_16x16x32_bf16 v[158:161], v[54:57], v[180:183], v[158:161]
	v_mfma_f32_16x16x32_bf16 v[154:157], v[66:69], v[176:179], v[154:157]
	v_mfma_f32_16x16x32_bf16 v[154:157], v[70:73], v[180:183], v[154:157]
	v_mfma_f32_16x16x32_bf16 v[138:141], v[50:53], v[186:189], v[138:141]
	v_mfma_f32_16x16x32_bf16 v[138:141], v[54:57], v[190:193], v[138:141]
	v_mfma_f32_16x16x32_bf16 v[134:137], v[66:69], v[186:189], v[134:137]
	v_mfma_f32_16x16x32_bf16 v[134:137], v[70:73], v[190:193], v[134:137]
	v_mfma_f32_16x16x32_bf16 v[118:121], v[50:53], v[194:197], v[118:121]
	v_mfma_f32_16x16x32_bf16 v[118:121], v[54:57], v[198:201], v[118:121]
	v_mfma_f32_16x16x32_bf16 v[114:117], v[66:69], v[194:197], v[114:117]
	v_mfma_f32_16x16x32_bf16 v[114:117], v[70:73], v[198:201], v[114:117]
	v_mfma_f32_16x16x32_bf16 v[98:101], v[50:53], v[202:205], v[98:101]
	v_mfma_f32_16x16x32_bf16 v[98:101], v[54:57], v[206:209], v[98:101]
	v_mfma_f32_16x16x32_bf16 v[94:97], v[66:69], v[202:205], v[94:97]
	v_mfma_f32_16x16x32_bf16 v[94:97], v[70:73], v[206:209], v[94:97]
	s_setprio 0
	s_setprio 1
	v_mfma_f32_16x16x32_bf16 v[150:153], v[90:93], v[176:179], v[150:153]
	v_mfma_f32_16x16x32_bf16 v[150:153], v[110:113], v[180:183], v[150:153]
	v_mfma_f32_16x16x32_bf16 v[146:149], v[126:129], v[176:179], v[146:149]
	v_mfma_f32_16x16x32_bf16 v[146:149], v[142:145], v[180:183], v[146:149]
	v_mfma_f32_16x16x32_bf16 v[130:133], v[90:93], v[186:189], v[130:133]
	v_mfma_f32_16x16x32_bf16 v[130:133], v[110:113], v[190:193], v[130:133]
	v_mfma_f32_16x16x32_bf16 v[122:125], v[126:129], v[186:189], v[122:125]
	v_mfma_f32_16x16x32_bf16 v[122:125], v[142:145], v[190:193], v[122:125]
	v_mfma_f32_16x16x32_bf16 v[106:109], v[90:93], v[194:197], v[106:109]
	v_mfma_f32_16x16x32_bf16 v[106:109], v[110:113], v[198:201], v[106:109]
	v_mfma_f32_16x16x32_bf16 v[102:105], v[126:129], v[194:197], v[102:105]
	v_mfma_f32_16x16x32_bf16 v[102:105], v[142:145], v[198:201], v[102:105]
	v_mfma_f32_16x16x32_bf16 v[86:89], v[90:93], v[202:205], v[86:89]
	v_mfma_f32_16x16x32_bf16 v[86:89], v[110:113], v[206:209], v[86:89]
	v_mfma_f32_16x16x32_bf16 v[82:85], v[126:129], v[202:205], v[82:85]
	v_mfma_f32_16x16x32_bf16 v[82:85], v[142:145], v[206:209], v[82:85]
	s_setprio 0
	s_barrier
	s_add_i32 s63, s63, s49
	v_lshl_add_u64 v[214:215], s[2:3], 0, v[0:1]
	s_mov_b32 m0, s63
	ds_read_b128 v[176:179], v213 offset:16384
	ds_read_b128 v[180:183], v213 offset:17408
	ds_read_b128 v[186:189], v213 offset:18432
	ds_read_b128 v[190:193], v213 offset:19456
	ds_read_b128 v[194:197], v213 offset:20480
	ds_read_b128 v[198:201], v213 offset:21504
	ds_read_b128 v[202:205], v213 offset:22528
	ds_read_b128 v[206:209], v213 offset:23552
	global_load_lds_dwordx4 v[214:215], off
	s_add_i32 m0, s63, 0x2000
	s_add_u32 s64, s2, 0x40000
	v_lshl_add_u64 v[216:217], s[2:3], 0, v[166:167]
	s_addc_u32 s65, s3, 0
	s_add_i32 s63, s66, s49
	global_load_lds_dwordx4 v[216:217], off
	v_lshl_add_u64 v[218:219], s[64:65], 0, v[0:1]
	s_mov_b32 m0, s63
	v_lshl_add_u64 v[220:221], s[44:45], 0, v[164:165]
	global_load_lds_dwordx4 v[218:219], off
	v_lshl_add_u64 v[218:219], s[64:65], 0, v[166:167]
	s_add_i32 m0, s63, 0x2000
	s_nop 0
	global_load_lds_dwordx4 v[218:219], off
	v_lshl_add_u64 v[218:219], s[44:45], 0, v[162:163]
	s_mov_b32 m0, s50
	s_nop 0
	global_load_lds_dwordx4 v[218:219], off
	s_mov_b32 m0, s51
	s_nop 0
	global_load_lds_dwordx4 v[220:221], off
	s_waitcnt vmcnt(8)
	s_waitcnt lgkmcnt(0)
	s_barrier
	s_setprio 1
	s_waitcnt lgkmcnt(0)
	v_mfma_f32_16x16x32_bf16 v[78:81], v[50:53], v[176:179], v[78:81]
	v_mfma_f32_16x16x32_bf16 v[78:81], v[54:57], v[180:183], v[78:81]
	v_mfma_f32_16x16x32_bf16 v[74:77], v[66:69], v[176:179], v[74:77]
	v_mfma_f32_16x16x32_bf16 v[74:77], v[70:73], v[180:183], v[74:77]
	v_mfma_f32_16x16x32_bf16 v[46:49], v[50:53], v[186:189], v[46:49]
	v_mfma_f32_16x16x32_bf16 v[46:49], v[54:57], v[190:193], v[46:49]
	v_mfma_f32_16x16x32_bf16 v[42:45], v[66:69], v[186:189], v[42:45]
	v_mfma_f32_16x16x32_bf16 v[42:45], v[70:73], v[190:193], v[42:45]
	v_mfma_f32_16x16x32_bf16 v[30:33], v[50:53], v[194:197], v[30:33]
	v_mfma_f32_16x16x32_bf16 v[30:33], v[54:57], v[198:201], v[30:33]
	v_mfma_f32_16x16x32_bf16 v[26:29], v[66:69], v[194:197], v[26:29]
	v_mfma_f32_16x16x32_bf16 v[26:29], v[70:73], v[198:201], v[26:29]
	v_mfma_f32_16x16x32_bf16 v[14:17], v[50:53], v[202:205], v[14:17]
	v_mfma_f32_16x16x32_bf16 v[14:17], v[54:57], v[206:209], v[14:17]
	v_mfma_f32_16x16x32_bf16 v[10:13], v[66:69], v[202:205], v[10:13]
	v_mfma_f32_16x16x32_bf16 v[10:13], v[70:73], v[206:209], v[10:13]
	s_setprio 0
	s_setprio 1
	v_mfma_f32_16x16x32_bf16 v[38:41], v[90:93], v[186:189], v[38:41]
	v_mfma_f32_16x16x32_bf16 v[38:41], v[110:113], v[190:193], v[38:41]
	v_mfma_f32_16x16x32_bf16 v[34:37], v[126:129], v[186:189], v[34:37]
	v_mfma_f32_16x16x32_bf16 v[34:37], v[142:145], v[190:193], v[34:37]
	v_mfma_f32_16x16x32_bf16 v[22:25], v[90:93], v[194:197], v[22:25]
	v_mfma_f32_16x16x32_bf16 v[22:25], v[110:113], v[198:201], v[22:25]
	v_mfma_f32_16x16x32_bf16 v[18:21], v[126:129], v[194:197], v[18:21]
	v_mfma_f32_16x16x32_bf16 v[18:21], v[142:145], v[198:201], v[18:21]
	v_mfma_f32_16x16x32_bf16 v[6:9], v[90:93], v[202:205], v[6:9]
	v_mfma_f32_16x16x32_bf16 v[6:9], v[110:113], v[206:209], v[6:9]
	v_mfma_f32_16x16x32_bf16 v[2:5], v[126:129], v[202:205], v[2:5]
	v_mfma_f32_16x16x32_bf16 v[2:5], v[142:145], v[206:209], v[2:5]
	v_mfma_f32_16x16x32_bf16 v[50:53], v[90:93], v[176:179], v[62:65]
	v_mfma_f32_16x16x32_bf16 v[50:53], v[110:113], v[180:183], v[50:53]
	v_mfma_f32_16x16x32_bf16 v[54:57], v[126:129], v[176:179], v[58:61]
	v_mfma_f32_16x16x32_bf16 v[54:57], v[142:145], v[180:183], v[54:57]
	s_setprio 0
	s_barrier
	s_add_i32 s63, 0, 0x18000
	s_add_i32 s64, 0, 0x1c000
	v_add_u32_e32 v70, s63, v211
	v_add_u32_e32 v142, s64, v211
	ds_read_b128 v[58:61], v70
	ds_read_b128 v[62:65], v70 offset:1024
	ds_read_b128 v[66:69], v70 offset:2048
	ds_read_b128 v[70:73], v70 offset:3072
	ds_read_b128 v[90:93], v142
	ds_read_b128 v[110:113], v142 offset:1024
	ds_read_b128 v[126:129], v142 offset:2048
	ds_read_b128 v[142:145], v142 offset:3072
	s_add_u32 s44, s44, 0x40000
	s_addc_u32 s45, s45, 0
	s_mov_b32 m0, s52
	v_lshl_add_u64 v[222:223], s[44:45], 0, v[162:163]
	ds_read_b128 v[176:179], v213 offset:32768
	ds_read_b128 v[180:183], v213 offset:33792
	ds_read_b128 v[186:189], v213 offset:34816
	ds_read_b128 v[190:193], v213 offset:35840
	ds_read_b128 v[194:197], v213 offset:36864
	ds_read_b128 v[198:201], v213 offset:37888
	ds_read_b128 v[202:205], v213 offset:38912
	ds_read_b128 v[206:209], v213 offset:39936
	global_load_lds_dwordx4 v[222:223], off
	v_lshl_add_u64 v[222:223], s[44:45], 0, v[164:165]
	s_mov_b32 m0, s53
	s_nop 0
	global_load_lds_dwordx4 v[222:223], off
	s_waitcnt vmcnt(8)
	s_waitcnt lgkmcnt(0)
	s_barrier
	s_setprio 1
	s_waitcnt lgkmcnt(0)
	v_mfma_f32_16x16x32_bf16 v[158:161], v[58:61], v[176:179], v[158:161]
	v_mfma_f32_16x16x32_bf16 v[158:161], v[62:65], v[180:183], v[158:161]
	v_mfma_f32_16x16x32_bf16 v[154:157], v[66:69], v[176:179], v[154:157]
	v_mfma_f32_16x16x32_bf16 v[154:157], v[70:73], v[180:183], v[154:157]
	v_mfma_f32_16x16x32_bf16 v[138:141], v[58:61], v[186:189], v[138:141]
	v_mfma_f32_16x16x32_bf16 v[138:141], v[62:65], v[190:193], v[138:141]
	v_mfma_f32_16x16x32_bf16 v[134:137], v[66:69], v[186:189], v[134:137]
	v_mfma_f32_16x16x32_bf16 v[134:137], v[70:73], v[190:193], v[134:137]
	v_mfma_f32_16x16x32_bf16 v[118:121], v[58:61], v[194:197], v[118:121]
	v_mfma_f32_16x16x32_bf16 v[118:121], v[62:65], v[198:201], v[118:121]
	v_mfma_f32_16x16x32_bf16 v[114:117], v[66:69], v[194:197], v[114:117]
	v_mfma_f32_16x16x32_bf16 v[114:117], v[70:73], v[198:201], v[114:117]
	v_mfma_f32_16x16x32_bf16 v[98:101], v[58:61], v[202:205], v[98:101]
	v_mfma_f32_16x16x32_bf16 v[98:101], v[62:65], v[206:209], v[98:101]
	v_mfma_f32_16x16x32_bf16 v[94:97], v[66:69], v[202:205], v[94:97]
	v_mfma_f32_16x16x32_bf16 v[94:97], v[70:73], v[206:209], v[94:97]
	s_setprio 0
	s_setprio 1
	v_mfma_f32_16x16x32_bf16 v[150:153], v[90:93], v[176:179], v[150:153]
	v_mfma_f32_16x16x32_bf16 v[150:153], v[110:113], v[180:183], v[150:153]
	v_mfma_f32_16x16x32_bf16 v[146:149], v[126:129], v[176:179], v[146:149]
	v_mfma_f32_16x16x32_bf16 v[146:149], v[142:145], v[180:183], v[146:149]
	v_mfma_f32_16x16x32_bf16 v[130:133], v[90:93], v[186:189], v[130:133]
	v_mfma_f32_16x16x32_bf16 v[130:133], v[110:113], v[190:193], v[130:133]
	v_mfma_f32_16x16x32_bf16 v[122:125], v[126:129], v[186:189], v[122:125]
	v_mfma_f32_16x16x32_bf16 v[122:125], v[142:145], v[190:193], v[122:125]
	v_mfma_f32_16x16x32_bf16 v[106:109], v[90:93], v[194:197], v[106:109]
	v_mfma_f32_16x16x32_bf16 v[106:109], v[110:113], v[198:201], v[106:109]
	v_mfma_f32_16x16x32_bf16 v[102:105], v[126:129], v[194:197], v[102:105]
	v_mfma_f32_16x16x32_bf16 v[102:105], v[142:145], v[198:201], v[102:105]
	v_mfma_f32_16x16x32_bf16 v[86:89], v[90:93], v[202:205], v[86:89]
	v_mfma_f32_16x16x32_bf16 v[86:89], v[110:113], v[206:209], v[86:89]
	v_mfma_f32_16x16x32_bf16 v[82:85], v[126:129], v[202:205], v[82:85]
	v_mfma_f32_16x16x32_bf16 v[82:85], v[142:145], v[206:209], v[82:85]
	s_setprio 0
	s_barrier
	s_add_i32 s44, s63, s49
	v_lshl_add_u64 v[214:215], v[214:215], 0, s[74:75]
	s_mov_b32 m0, s44
	ds_read_b128 v[176:179], v213 offset:49152
	ds_read_b128 v[180:183], v213 offset:50176
	ds_read_b128 v[186:189], v213 offset:51200
	ds_read_b128 v[190:193], v213 offset:52224
	ds_read_b128 v[194:197], v213 offset:53248
	ds_read_b128 v[198:201], v213 offset:54272
	ds_read_b128 v[202:205], v213 offset:55296
	ds_read_b128 v[206:209], v213 offset:56320
	global_load_lds_dwordx4 v[214:215], off
	s_add_i32 m0, s44, 0x2000
	s_add_u32 s2, s2, 0x40080
	v_lshl_add_u64 v[214:215], v[216:217], 0, s[74:75]
	s_addc_u32 s3, s3, 0
	s_add_i32 s44, s64, s49
	global_load_lds_dwordx4 v[214:215], off
	v_lshl_add_u64 v[214:215], s[2:3], 0, v[0:1]
	s_mov_b32 m0, s44
	s_nop 0
	global_load_lds_dwordx4 v[214:215], off
	v_lshl_add_u64 v[214:215], s[2:3], 0, v[166:167]
	s_add_i32 m0, s44, 0x2000
	s_nop 0
	global_load_lds_dwordx4 v[214:215], off
	v_lshl_add_u64 v[214:215], v[218:219], 0, s[74:75]
	s_mov_b32 m0, s55
	s_nop 0
	global_load_lds_dwordx4 v[214:215], off
	v_lshl_add_u64 v[214:215], v[220:221], 0, s[74:75]
	s_mov_b32 m0, s56
	s_nop 0
	global_load_lds_dwordx4 v[214:215], off
	s_waitcnt vmcnt(8)
	s_waitcnt lgkmcnt(0)
	s_barrier
	s_setprio 1
	s_waitcnt lgkmcnt(0)
	v_mfma_f32_16x16x32_bf16 v[78:81], v[58:61], v[176:179], v[78:81]
	v_mfma_f32_16x16x32_bf16 v[78:81], v[62:65], v[180:183], v[78:81]
	v_mfma_f32_16x16x32_bf16 v[74:77], v[66:69], v[176:179], v[74:77]
	v_mfma_f32_16x16x32_bf16 v[74:77], v[70:73], v[180:183], v[74:77]
	v_mfma_f32_16x16x32_bf16 v[46:49], v[58:61], v[186:189], v[46:49]
	v_mfma_f32_16x16x32_bf16 v[46:49], v[62:65], v[190:193], v[46:49]
	v_mfma_f32_16x16x32_bf16 v[42:45], v[66:69], v[186:189], v[42:45]
	v_mfma_f32_16x16x32_bf16 v[42:45], v[70:73], v[190:193], v[42:45]
	v_mfma_f32_16x16x32_bf16 v[30:33], v[58:61], v[194:197], v[30:33]
	v_mfma_f32_16x16x32_bf16 v[30:33], v[62:65], v[198:201], v[30:33]
	v_mfma_f32_16x16x32_bf16 v[26:29], v[66:69], v[194:197], v[26:29]
	v_mfma_f32_16x16x32_bf16 v[26:29], v[70:73], v[198:201], v[26:29]
	v_mfma_f32_16x16x32_bf16 v[14:17], v[58:61], v[202:205], v[14:17]
	v_mfma_f32_16x16x32_bf16 v[14:17], v[62:65], v[206:209], v[14:17]
	v_mfma_f32_16x16x32_bf16 v[10:13], v[66:69], v[202:205], v[10:13]
	v_mfma_f32_16x16x32_bf16 v[10:13], v[70:73], v[206:209], v[10:13]
	s_setprio 0
	s_setprio 1
	v_mfma_f32_16x16x32_bf16 v[50:53], v[90:93], v[176:179], v[50:53]
	v_mfma_f32_16x16x32_bf16 v[62:65], v[110:113], v[180:183], v[50:53]
	v_mfma_f32_16x16x32_bf16 v[50:53], v[126:129], v[176:179], v[54:57]
	v_mfma_f32_16x16x32_bf16 v[38:41], v[90:93], v[186:189], v[38:41]
	v_mfma_f32_16x16x32_bf16 v[34:37], v[126:129], v[186:189], v[34:37]
	v_mfma_f32_16x16x32_bf16 v[22:25], v[90:93], v[194:197], v[22:25]
	v_mfma_f32_16x16x32_bf16 v[18:21], v[126:129], v[194:197], v[18:21]
	v_mfma_f32_16x16x32_bf16 v[6:9], v[90:93], v[202:205], v[6:9]
	v_mfma_f32_16x16x32_bf16 v[2:5], v[126:129], v[202:205], v[2:5]
	v_mfma_f32_16x16x32_bf16 v[58:61], v[142:145], v[180:183], v[50:53]
	v_mfma_f32_16x16x32_bf16 v[38:41], v[110:113], v[190:193], v[38:41]
	v_mfma_f32_16x16x32_bf16 v[34:37], v[142:145], v[190:193], v[34:37]
	v_mfma_f32_16x16x32_bf16 v[22:25], v[110:113], v[198:201], v[22:25]
	v_mfma_f32_16x16x32_bf16 v[18:21], v[142:145], v[198:201], v[18:21]
	v_mfma_f32_16x16x32_bf16 v[6:9], v[110:113], v[206:209], v[6:9]
	v_mfma_f32_16x16x32_bf16 v[2:5], v[142:145], v[206:209], v[2:5]
	s_setprio 0
	s_barrier
	s_add_i32 s62, s62, 2
	s_add_u32 s8, s8, 0x100
	s_addc_u32 s9, s9, 0
	s_add_u32 s33, s33, 0x100
	s_addc_u32 s61, s61, 0
	s_cmp_gt_u32 s62, 13
	s_cbranch_scc0 .LBB0_469
	s_and_b64 vcc, exec, s[28:29]
	s_cbranch_vccz .LBB0_472
	s_barrier

.LBB0_556:
	s_add_u32 s4, s26, 0x80
	s_addc_u32 s5, s27, 0
	s_add_u32 s26, s2, 0x100
	s_addc_u32 s27, s3, 0
	s_mov_b32 s2, 0
	s_add_i32 s33, s2, 2
	s_add_u32 s45, s4, 0x80
	s_addc_u32 s3, s5, 0
	s_add_i32 s48, 0, 0x10000
	s_cmp_eq_u32 s40, s2
	s_cselect_b32 s3, s23, s3
	s_cselect_b32 s2, s22, s45
	s_cselect_b32 s47, s25, s27
	s_cselect_b32 s46, s24, s26
	s_add_i32 s45, 0, 0x14000
	v_add_u32_e32 v70, s48, v199
	v_add_u32_e32 v158, s45, v199
	ds_read_b128 v[58:61], v70
	ds_read_b128 v[62:65], v70 offset:1024
	ds_read_b128 v[66:69], v70 offset:2048
	ds_read_b128 v[70:73], v70 offset:3072
	ds_read_b128 v[138:141], v158
	ds_read_b128 v[150:153], v158 offset:1024
	ds_read_b128 v[154:157], v158 offset:2048
	ds_read_b128 v[158:161], v158 offset:3072
	v_lshl_add_u64 v[196:197], s[4:5], 0, v[176:177]
	s_add_i32 m0, s30, 0xc000
	ds_read_b128 v[162:165], v201
	ds_read_b128 v[166:169], v201 offset:1024
	ds_read_b128 v[180:183], v201 offset:2048
	ds_read_b128 v[184:187], v201 offset:3072
	ds_read_b128 v[188:191], v201 offset:4096
	ds_read_b128 v[192:195], v201 offset:5120
	ds_read_b128 v[202:205], v201 offset:6144
	ds_read_b128 v[206:209], v201 offset:7168
	global_load_lds_dwordx4 v[196:197], off
	v_lshl_add_u64 v[196:197], s[4:5], 0, v[178:179]
	s_add_i32 m0, s30, 0xe000
	s_nop 0
	global_load_lds_dwordx4 v[196:197], off
	s_waitcnt vmcnt(8)
	s_waitcnt lgkmcnt(0)
	s_barrier
	s_setprio 1
	s_waitcnt lgkmcnt(0)
	v_mfma_f32_16x16x32_bf16 v[146:149], v[58:61], v[162:165], 0
	v_mfma_f32_16x16x32_bf16 v[146:149], v[62:65], v[166:169], v[146:149]
	v_mfma_f32_16x16x32_bf16 v[142:145], v[66:69], v[162:165], 0
	v_mfma_f32_16x16x32_bf16 v[142:145], v[70:73], v[166:169], v[142:145]
	v_mfma_f32_16x16x32_bf16 v[126:129], v[58:61], v[180:183], 0
	v_mfma_f32_16x16x32_bf16 v[126:129], v[62:65], v[184:187], v[126:129]
	v_mfma_f32_16x16x32_bf16 v[122:125], v[66:69], v[180:183], 0
	v_mfma_f32_16x16x32_bf16 v[122:125], v[70:73], v[184:187], v[122:125]
	v_mfma_f32_16x16x32_bf16 v[110:113], v[58:61], v[188:191], 0
	v_mfma_f32_16x16x32_bf16 v[110:113], v[62:65], v[192:195], v[110:113]
	v_mfma_f32_16x16x32_bf16 v[106:109], v[66:69], v[188:191], 0
	v_mfma_f32_16x16x32_bf16 v[106:109], v[70:73], v[192:195], v[106:109]
	v_mfma_f32_16x16x32_bf16 v[94:97], v[58:61], v[202:205], 0
	v_mfma_f32_16x16x32_bf16 v[94:97], v[62:65], v[206:209], v[94:97]
	v_mfma_f32_16x16x32_bf16 v[90:93], v[66:69], v[202:205], 0
	v_mfma_f32_16x16x32_bf16 v[90:93], v[70:73], v[206:209], v[90:93]
	s_setprio 0
	s_setprio 1
	v_mfma_f32_16x16x32_bf16 v[134:137], v[138:141], v[162:165], 0
	v_mfma_f32_16x16x32_bf16 v[134:137], v[150:153], v[166:169], v[134:137]
	v_mfma_f32_16x16x32_bf16 v[130:133], v[154:157], v[162:165], 0
	v_mfma_f32_16x16x32_bf16 v[130:133], v[158:161], v[166:169], v[130:133]
	v_mfma_f32_16x16x32_bf16 v[118:121], v[138:141], v[180:183], 0
	v_mfma_f32_16x16x32_bf16 v[118:121], v[150:153], v[184:187], v[118:121]
	v_mfma_f32_16x16x32_bf16 v[114:117], v[154:157], v[180:183], 0
	v_mfma_f32_16x16x32_bf16 v[114:117], v[158:161], v[184:187], v[114:117]
	v_mfma_f32_16x16x32_bf16 v[102:105], v[138:141], v[188:191], 0
	v_mfma_f32_16x16x32_bf16 v[102:105], v[150:153], v[192:195], v[102:105]
	v_mfma_f32_16x16x32_bf16 v[98:101], v[154:157], v[188:191], 0
	v_mfma_f32_16x16x32_bf16 v[98:101], v[158:161], v[192:195], v[98:101]
	v_mfma_f32_16x16x32_bf16 v[86:89], v[138:141], v[202:205], 0
	v_mfma_f32_16x16x32_bf16 v[86:89], v[150:153], v[206:209], v[86:89]
	v_mfma_f32_16x16x32_bf16 v[82:85], v[154:157], v[202:205], 0
	v_mfma_f32_16x16x32_bf16 v[82:85], v[158:161], v[206:209], v[82:85]
	s_setprio 0
	s_barrier
	s_add_i32 s48, s48, s29
	v_lshl_add_u64 v[196:197], s[46:47], 0, v[0:1]
	s_mov_b32 m0, s48
	ds_read_b128 v[162:165], v201 offset:16384
	ds_read_b128 v[166:169], v201 offset:17408
	ds_read_b128 v[180:183], v201 offset:18432
	ds_read_b128 v[184:187], v201 offset:19456
	ds_read_b128 v[188:191], v201 offset:20480
	ds_read_b128 v[192:195], v201 offset:21504
	ds_read_b128 v[202:205], v201 offset:22528
	ds_read_b128 v[206:209], v201 offset:23552
	global_load_lds_dwordx4 v[196:197], off
	s_add_i32 m0, s48, 0x2000
	v_lshl_add_u64 v[210:211], s[46:47], 0, v[170:171]
	s_add_u32 s46, s46, s12
	s_addc_u32 s47, s47, 0
	s_add_i32 s45, s45, s29
	global_load_lds_dwordx4 v[210:211], off
	v_lshl_add_u64 v[212:213], s[46:47], 0, v[0:1]
	s_mov_b32 m0, s45
	v_lshl_add_u64 v[214:215], s[46:47], 0, v[170:171]
	global_load_lds_dwordx4 v[212:213], off
	s_add_i32 m0, s45, 0x2000
	v_lshl_add_u64 v[216:217], s[2:3], 0, v[174:175]
	global_load_lds_dwordx4 v[214:215], off
	s_mov_b32 m0, s30
	v_lshl_add_u64 v[218:219], s[2:3], 0, v[172:173]
	global_load_lds_dwordx4 v[216:217], off
	s_mov_b32 m0, s31
	s_nop 0
	global_load_lds_dwordx4 v[218:219], off
	s_waitcnt vmcnt(8)
	s_waitcnt lgkmcnt(0)
	s_barrier
	s_setprio 1
	s_waitcnt lgkmcnt(0)
	v_mfma_f32_16x16x32_bf16 v[78:81], v[58:61], v[162:165], 0
	v_mfma_f32_16x16x32_bf16 v[78:81], v[62:65], v[166:169], v[78:81]
	v_mfma_f32_16x16x32_bf16 v[74:77], v[66:69], v[162:165], 0
	v_mfma_f32_16x16x32_bf16 v[74:77], v[70:73], v[166:169], v[74:77]
	v_mfma_f32_16x16x32_bf16 v[46:49], v[58:61], v[180:183], 0
	v_mfma_f32_16x16x32_bf16 v[46:49], v[62:65], v[184:187], v[46:49]
	v_mfma_f32_16x16x32_bf16 v[42:45], v[66:69], v[180:183], 0
	v_mfma_f32_16x16x32_bf16 v[42:45], v[70:73], v[184:187], v[42:45]
	v_mfma_f32_16x16x32_bf16 v[30:33], v[58:61], v[188:191], 0
	v_mfma_f32_16x16x32_bf16 v[30:33], v[62:65], v[192:195], v[30:33]
	v_mfma_f32_16x16x32_bf16 v[26:29], v[66:69], v[188:191], 0
	v_mfma_f32_16x16x32_bf16 v[26:29], v[70:73], v[192:195], v[26:29]
	v_mfma_f32_16x16x32_bf16 v[14:17], v[58:61], v[202:205], 0
	v_mfma_f32_16x16x32_bf16 v[14:17], v[62:65], v[206:209], v[14:17]
	v_mfma_f32_16x16x32_bf16 v[10:13], v[66:69], v[202:205], 0
	v_mfma_f32_16x16x32_bf16 v[10:13], v[70:73], v[206:209], v[10:13]
	s_setprio 0
	s_setprio 1
	v_mfma_f32_16x16x32_bf16 v[54:57], v[138:141], v[162:165], 0
	v_mfma_f32_16x16x32_bf16 v[54:57], v[150:153], v[166:169], v[54:57]
	v_mfma_f32_16x16x32_bf16 v[50:53], v[154:157], v[162:165], 0
	v_mfma_f32_16x16x32_bf16 v[50:53], v[158:161], v[166:169], v[50:53]
	v_mfma_f32_16x16x32_bf16 v[38:41], v[138:141], v[180:183], 0
	v_mfma_f32_16x16x32_bf16 v[38:41], v[150:153], v[184:187], v[38:41]
	v_mfma_f32_16x16x32_bf16 v[34:37], v[154:157], v[180:183], 0
	v_mfma_f32_16x16x32_bf16 v[34:37], v[158:161], v[184:187], v[34:37]
	v_mfma_f32_16x16x32_bf16 v[22:25], v[138:141], v[188:191], 0
	v_mfma_f32_16x16x32_bf16 v[22:25], v[150:153], v[192:195], v[22:25]
	v_mfma_f32_16x16x32_bf16 v[18:21], v[154:157], v[188:191], 0
	v_mfma_f32_16x16x32_bf16 v[18:21], v[158:161], v[192:195], v[18:21]
	v_mfma_f32_16x16x32_bf16 v[6:9], v[138:141], v[202:205], 0
	v_mfma_f32_16x16x32_bf16 v[6:9], v[150:153], v[206:209], v[6:9]
	v_mfma_f32_16x16x32_bf16 v[2:5], v[154:157], v[202:205], 0
	v_mfma_f32_16x16x32_bf16 v[2:5], v[158:161], v[206:209], v[2:5]
	s_setprio 0
	s_barrier
	s_add_i32 s45, 0, 0x18000
	s_add_i32 s46, 0, 0x1c000
	v_add_u32_e32 v70, s45, v199
	v_add_u32_e32 v158, s46, v199
	ds_read_b128 v[58:61], v70
	ds_read_b128 v[62:65], v70 offset:1024
	ds_read_b128 v[66:69], v70 offset:2048
	ds_read_b128 v[70:73], v70 offset:3072
	ds_read_b128 v[138:141], v158
	ds_read_b128 v[150:153], v158 offset:1024
	ds_read_b128 v[154:157], v158 offset:2048
	ds_read_b128 v[158:161], v158 offset:3072
	s_add_u32 s2, s2, s12
	s_addc_u32 s3, s3, 0
	s_mov_b32 m0, s34
	v_lshl_add_u64 v[220:221], s[2:3], 0, v[174:175]
	ds_read_b128 v[162:165], v201 offset:32768
	ds_read_b128 v[166:169], v201 offset:33792
	ds_read_b128 v[180:183], v201 offset:34816
	ds_read_b128 v[184:187], v201 offset:35840
	ds_read_b128 v[188:191], v201 offset:36864
	ds_read_b128 v[192:195], v201 offset:37888
	ds_read_b128 v[202:205], v201 offset:38912
	ds_read_b128 v[206:209], v201 offset:39936
	global_load_lds_dwordx4 v[220:221], off
	v_lshl_add_u64 v[220:221], s[2:3], 0, v[172:173]
	s_mov_b32 m0, s35
	s_nop 0
	global_load_lds_dwordx4 v[220:221], off
	s_waitcnt vmcnt(8)
	s_waitcnt lgkmcnt(0)
	s_barrier
	s_setprio 1
	s_waitcnt lgkmcnt(0)
	v_mfma_f32_16x16x32_bf16 v[146:149], v[58:61], v[162:165], v[146:149]
	v_mfma_f32_16x16x32_bf16 v[146:149], v[62:65], v[166:169], v[146:149]
	v_mfma_f32_16x16x32_bf16 v[142:145], v[66:69], v[162:165], v[142:145]
	v_mfma_f32_16x16x32_bf16 v[142:145], v[70:73], v[166:169], v[142:145]
	v_mfma_f32_16x16x32_bf16 v[126:129], v[58:61], v[180:183], v[126:129]
	v_mfma_f32_16x16x32_bf16 v[126:129], v[62:65], v[184:187], v[126:129]
	v_mfma_f32_16x16x32_bf16 v[122:125], v[66:69], v[180:183], v[122:125]
	v_mfma_f32_16x16x32_bf16 v[122:125], v[70:73], v[184:187], v[122:125]
	v_mfma_f32_16x16x32_bf16 v[110:113], v[58:61], v[188:191], v[110:113]
	v_mfma_f32_16x16x32_bf16 v[110:113], v[62:65], v[192:195], v[110:113]
	v_mfma_f32_16x16x32_bf16 v[106:109], v[66:69], v[188:191], v[106:109]
	v_mfma_f32_16x16x32_bf16 v[106:109], v[70:73], v[192:195], v[106:109]
	v_mfma_f32_16x16x32_bf16 v[94:97], v[58:61], v[202:205], v[94:97]
	v_mfma_f32_16x16x32_bf16 v[94:97], v[62:65], v[206:209], v[94:97]
	v_mfma_f32_16x16x32_bf16 v[90:93], v[66:69], v[202:205], v[90:93]
	v_mfma_f32_16x16x32_bf16 v[90:93], v[70:73], v[206:209], v[90:93]
	s_setprio 0
	s_setprio 1
	v_mfma_f32_16x16x32_bf16 v[134:137], v[138:141], v[162:165], v[134:137]
	v_mfma_f32_16x16x32_bf16 v[134:137], v[150:153], v[166:169], v[134:137]
	v_mfma_f32_16x16x32_bf16 v[130:133], v[154:157], v[162:165], v[130:133]
	v_mfma_f32_16x16x32_bf16 v[130:133], v[158:161], v[166:169], v[130:133]
	v_mfma_f32_16x16x32_bf16 v[118:121], v[138:141], v[180:183], v[118:121]
	v_mfma_f32_16x16x32_bf16 v[118:121], v[150:153], v[184:187], v[118:121]
	v_mfma_f32_16x16x32_bf16 v[114:117], v[154:157], v[180:183], v[114:117]
	v_mfma_f32_16x16x32_bf16 v[114:117], v[158:161], v[184:187], v[114:117]
	v_mfma_f32_16x16x32_bf16 v[102:105], v[138:141], v[188:191], v[102:105]
	v_mfma_f32_16x16x32_bf16 v[102:105], v[150:153], v[192:195], v[102:105]
	v_mfma_f32_16x16x32_bf16 v[98:101], v[154:157], v[188:191], v[98:101]
	v_mfma_f32_16x16x32_bf16 v[98:101], v[158:161], v[192:195], v[98:101]
	v_mfma_f32_16x16x32_bf16 v[86:89], v[138:141], v[202:205], v[86:89]
	v_mfma_f32_16x16x32_bf16 v[86:89], v[150:153], v[206:209], v[86:89]
	v_mfma_f32_16x16x32_bf16 v[82:85], v[154:157], v[202:205], v[82:85]
	v_mfma_f32_16x16x32_bf16 v[82:85], v[158:161], v[206:209], v[82:85]
	s_setprio 0
	s_barrier
	s_add_i32 s2, s45, s29
	v_lshl_add_u64 v[196:197], v[196:197], 0, s[74:75]
	s_mov_b32 m0, s2
	ds_read_b128 v[162:165], v201 offset:49152
	ds_read_b128 v[166:169], v201 offset:50176
	ds_read_b128 v[180:183], v201 offset:51200
	ds_read_b128 v[184:187], v201 offset:52224
	ds_read_b128 v[188:191], v201 offset:53248
	ds_read_b128 v[192:195], v201 offset:54272
	ds_read_b128 v[202:205], v201 offset:55296
	ds_read_b128 v[206:209], v201 offset:56320
	global_load_lds_dwordx4 v[196:197], off
	v_lshl_add_u64 v[196:197], v[210:211], 0, s[74:75]
	s_add_i32 m0, s2, 0x2000
	s_add_i32 s2, s46, s29
	global_load_lds_dwordx4 v[196:197], off
	v_lshl_add_u64 v[196:197], v[212:213], 0, s[74:75]
	s_mov_b32 m0, s2
	s_nop 0
	global_load_lds_dwordx4 v[196:197], off
	v_lshl_add_u64 v[196:197], v[214:215], 0, s[74:75]
	s_add_i32 m0, s2, 0x2000
	s_nop 0
	global_load_lds_dwordx4 v[196:197], off
	v_lshl_add_u64 v[196:197], v[216:217], 0, s[74:75]
	s_mov_b32 m0, s38
	s_nop 0
	global_load_lds_dwordx4 v[196:197], off
	v_lshl_add_u64 v[196:197], v[218:219], 0, s[74:75]
	s_mov_b32 m0, s39
	s_nop 0
	global_load_lds_dwordx4 v[196:197], off
	s_waitcnt vmcnt(8)
	s_waitcnt lgkmcnt(0)
	s_barrier
	s_setprio 1
	s_waitcnt lgkmcnt(0)
	v_mfma_f32_16x16x32_bf16 v[78:81], v[58:61], v[162:165], v[78:81]
	v_mfma_f32_16x16x32_bf16 v[78:81], v[62:65], v[166:169], v[78:81]
	v_mfma_f32_16x16x32_bf16 v[74:77], v[66:69], v[162:165], v[74:77]
	v_mfma_f32_16x16x32_bf16 v[74:77], v[70:73], v[166:169], v[74:77]
	v_mfma_f32_16x16x32_bf16 v[46:49], v[58:61], v[180:183], v[46:49]
	v_mfma_f32_16x16x32_bf16 v[46:49], v[62:65], v[184:187], v[46:49]
	v_mfma_f32_16x16x32_bf16 v[42:45], v[66:69], v[180:183], v[42:45]
	v_mfma_f32_16x16x32_bf16 v[42:45], v[70:73], v[184:187], v[42:45]
	v_mfma_f32_16x16x32_bf16 v[30:33], v[58:61], v[188:191], v[30:33]
	v_mfma_f32_16x16x32_bf16 v[30:33], v[62:65], v[192:195], v[30:33]
	v_mfma_f32_16x16x32_bf16 v[26:29], v[66:69], v[188:191], v[26:29]
	v_mfma_f32_16x16x32_bf16 v[26:29], v[70:73], v[192:195], v[26:29]
	v_mfma_f32_16x16x32_bf16 v[14:17], v[58:61], v[202:205], v[14:17]
	v_mfma_f32_16x16x32_bf16 v[14:17], v[62:65], v[206:209], v[14:17]
	v_mfma_f32_16x16x32_bf16 v[10:13], v[66:69], v[202:205], v[10:13]
	v_mfma_f32_16x16x32_bf16 v[10:13], v[70:73], v[206:209], v[10:13]
	s_setprio 0
	s_setprio 1
	v_mfma_f32_16x16x32_bf16 v[54:57], v[138:141], v[162:165], v[54:57]
	v_mfma_f32_16x16x32_bf16 v[54:57], v[150:153], v[166:169], v[54:57]
	v_mfma_f32_16x16x32_bf16 v[50:53], v[154:157], v[162:165], v[50:53]
	v_mfma_f32_16x16x32_bf16 v[50:53], v[158:161], v[166:169], v[50:53]
	v_mfma_f32_16x16x32_bf16 v[38:41], v[138:141], v[180:183], v[38:41]
	v_mfma_f32_16x16x32_bf16 v[38:41], v[150:153], v[184:187], v[38:41]
	v_mfma_f32_16x16x32_bf16 v[34:37], v[154:157], v[180:183], v[34:37]
	v_mfma_f32_16x16x32_bf16 v[34:37], v[158:161], v[184:187], v[34:37]
	v_mfma_f32_16x16x32_bf16 v[22:25], v[138:141], v[188:191], v[22:25]
	v_mfma_f32_16x16x32_bf16 v[22:25], v[150:153], v[192:195], v[22:25]
	v_mfma_f32_16x16x32_bf16 v[18:21], v[154:157], v[188:191], v[18:21]
	v_mfma_f32_16x16x32_bf16 v[18:21], v[158:161], v[192:195], v[18:21]
	v_mfma_f32_16x16x32_bf16 v[6:9], v[138:141], v[202:205], v[6:9]
	v_mfma_f32_16x16x32_bf16 v[6:9], v[150:153], v[206:209], v[6:9]
	v_mfma_f32_16x16x32_bf16 v[2:5], v[154:157], v[202:205], v[2:5]
	v_mfma_f32_16x16x32_bf16 v[2:5], v[158:161], v[206:209], v[2:5]
	s_setprio 0
	s_barrier
	s_add_u32 s4, s4, 0x100
	s_addc_u32 s5, s5, 0
	s_add_u32 s26, s26, 0x100
	s_addc_u32 s27, s27, 0
	s_cmp_ge_u32 s33, s37
	s_mov_b32 s2, s33
.LBB0_557:
	s_add_i32 s33, s2, 2
	s_add_u32 s45, s4, 0x80
	s_addc_u32 s3, s5, 0
	s_add_i32 s48, 0, 0x10000
	s_cmp_eq_u32 s40, s2
	s_cselect_b32 s3, s23, s3
	s_cselect_b32 s2, s22, s45
	s_cselect_b32 s47, s25, s27
	s_cselect_b32 s46, s24, s26
	s_add_i32 s45, 0, 0x14000
	v_add_u32_e32 v70, s48, v199
	v_add_u32_e32 v158, s45, v199
	ds_read_b128 v[58:61], v70
	ds_read_b128 v[62:65], v70 offset:1024
	ds_read_b128 v[66:69], v70 offset:2048
	ds_read_b128 v[70:73], v70 offset:3072
	ds_read_b128 v[138:141], v158
	ds_read_b128 v[150:153], v158 offset:1024
	ds_read_b128 v[154:157], v158 offset:2048
	ds_read_b128 v[158:161], v158 offset:3072
	v_lshl_add_u64 v[196:197], s[4:5], 0, v[176:177]
	s_add_i32 m0, s30, 0xc000
	ds_read_b128 v[162:165], v201
	ds_read_b128 v[166:169], v201 offset:1024
	ds_read_b128 v[180:183], v201 offset:2048
	ds_read_b128 v[184:187], v201 offset:3072
	ds_read_b128 v[188:191], v201 offset:4096
	ds_read_b128 v[192:195], v201 offset:5120
	ds_read_b128 v[202:205], v201 offset:6144
	ds_read_b128 v[206:209], v201 offset:7168
	global_load_lds_dwordx4 v[196:197], off
	v_lshl_add_u64 v[196:197], s[4:5], 0, v[178:179]
	s_add_i32 m0, s30, 0xe000
	s_nop 0
	global_load_lds_dwordx4 v[196:197], off
	s_waitcnt vmcnt(8)
	s_waitcnt lgkmcnt(0)
	s_barrier
	s_setprio 1
	s_waitcnt lgkmcnt(0)
	v_mfma_f32_16x16x32_bf16 v[146:149], v[58:61], v[162:165], v[146:149]
	v_mfma_f32_16x16x32_bf16 v[146:149], v[62:65], v[166:169], v[146:149]
	v_mfma_f32_16x16x32_bf16 v[142:145], v[66:69], v[162:165], v[142:145]
	v_mfma_f32_16x16x32_bf16 v[142:145], v[70:73], v[166:169], v[142:145]
	v_mfma_f32_16x16x32_bf16 v[126:129], v[58:61], v[180:183], v[126:129]
	v_mfma_f32_16x16x32_bf16 v[126:129], v[62:65], v[184:187], v[126:129]
	v_mfma_f32_16x16x32_bf16 v[122:125], v[66:69], v[180:183], v[122:125]
	v_mfma_f32_16x16x32_bf16 v[122:125], v[70:73], v[184:187], v[122:125]
	v_mfma_f32_16x16x32_bf16 v[110:113], v[58:61], v[188:191], v[110:113]
	v_mfma_f32_16x16x32_bf16 v[110:113], v[62:65], v[192:195], v[110:113]
	v_mfma_f32_16x16x32_bf16 v[106:109], v[66:69], v[188:191], v[106:109]
	v_mfma_f32_16x16x32_bf16 v[106:109], v[70:73], v[192:195], v[106:109]
	v_mfma_f32_16x16x32_bf16 v[94:97], v[58:61], v[202:205], v[94:97]
	v_mfma_f32_16x16x32_bf16 v[94:97], v[62:65], v[206:209], v[94:97]
	v_mfma_f32_16x16x32_bf16 v[90:93], v[66:69], v[202:205], v[90:93]
	v_mfma_f32_16x16x32_bf16 v[90:93], v[70:73], v[206:209], v[90:93]
	s_setprio 0
	s_setprio 1
	v_mfma_f32_16x16x32_bf16 v[134:137], v[138:141], v[162:165], v[134:137]
	v_mfma_f32_16x16x32_bf16 v[134:137], v[150:153], v[166:169], v[134:137]
	v_mfma_f32_16x16x32_bf16 v[130:133], v[154:157], v[162:165], v[130:133]
	v_mfma_f32_16x16x32_bf16 v[130:133], v[158:161], v[166:169], v[130:133]
	v_mfma_f32_16x16x32_bf16 v[118:121], v[138:141], v[180:183], v[118:121]
	v_mfma_f32_16x16x32_bf16 v[118:121], v[150:153], v[184:187], v[118:121]
	v_mfma_f32_16x16x32_bf16 v[114:117], v[154:157], v[180:183], v[114:117]
	v_mfma_f32_16x16x32_bf16 v[114:117], v[158:161], v[184:187], v[114:117]
	v_mfma_f32_16x16x32_bf16 v[102:105], v[138:141], v[188:191], v[102:105]
	v_mfma_f32_16x16x32_bf16 v[102:105], v[150:153], v[192:195], v[102:105]
	v_mfma_f32_16x16x32_bf16 v[98:101], v[154:157], v[188:191], v[98:101]
	v_mfma_f32_16x16x32_bf16 v[98:101], v[158:161], v[192:195], v[98:101]
	v_mfma_f32_16x16x32_bf16 v[86:89], v[138:141], v[202:205], v[86:89]
	v_mfma_f32_16x16x32_bf16 v[86:89], v[150:153], v[206:209], v[86:89]
	v_mfma_f32_16x16x32_bf16 v[82:85], v[154:157], v[202:205], v[82:85]
	v_mfma_f32_16x16x32_bf16 v[82:85], v[158:161], v[206:209], v[82:85]
	s_setprio 0
	s_barrier
	s_add_i32 s48, s48, s29
	v_lshl_add_u64 v[196:197], s[46:47], 0, v[0:1]
	s_mov_b32 m0, s48
	ds_read_b128 v[162:165], v201 offset:16384
	ds_read_b128 v[166:169], v201 offset:17408
	ds_read_b128 v[180:183], v201 offset:18432
	ds_read_b128 v[184:187], v201 offset:19456
	ds_read_b128 v[188:191], v201 offset:20480
	ds_read_b128 v[192:195], v201 offset:21504
	ds_read_b128 v[202:205], v201 offset:22528
	ds_read_b128 v[206:209], v201 offset:23552
	global_load_lds_dwordx4 v[196:197], off
	s_add_i32 m0, s48, 0x2000
	v_lshl_add_u64 v[210:211], s[46:47], 0, v[170:171]
	s_add_u32 s46, s46, s12
	s_addc_u32 s47, s47, 0
	s_add_i32 s45, s45, s29
	global_load_lds_dwordx4 v[210:211], off
	v_lshl_add_u64 v[212:213], s[46:47], 0, v[0:1]
	s_mov_b32 m0, s45
	v_lshl_add_u64 v[214:215], s[46:47], 0, v[170:171]
	global_load_lds_dwordx4 v[212:213], off
	s_add_i32 m0, s45, 0x2000
	v_lshl_add_u64 v[216:217], s[2:3], 0, v[174:175]
	global_load_lds_dwordx4 v[214:215], off
	s_mov_b32 m0, s30
	v_lshl_add_u64 v[218:219], s[2:3], 0, v[172:173]
	global_load_lds_dwordx4 v[216:217], off
	s_mov_b32 m0, s31
	s_nop 0
	global_load_lds_dwordx4 v[218:219], off
	s_waitcnt vmcnt(8)
	s_waitcnt lgkmcnt(0)
	s_barrier
	s_setprio 1
	s_waitcnt lgkmcnt(0)
	v_mfma_f32_16x16x32_bf16 v[78:81], v[58:61], v[162:165], v[78:81]
	v_mfma_f32_16x16x32_bf16 v[78:81], v[62:65], v[166:169], v[78:81]
	v_mfma_f32_16x16x32_bf16 v[74:77], v[66:69], v[162:165], v[74:77]
	v_mfma_f32_16x16x32_bf16 v[74:77], v[70:73], v[166:169], v[74:77]
	v_mfma_f32_16x16x32_bf16 v[46:49], v[58:61], v[180:183], v[46:49]
	v_mfma_f32_16x16x32_bf16 v[46:49], v[62:65], v[184:187], v[46:49]
	v_mfma_f32_16x16x32_bf16 v[42:45], v[66:69], v[180:183], v[42:45]
	v_mfma_f32_16x16x32_bf16 v[42:45], v[70:73], v[184:187], v[42:45]
	v_mfma_f32_16x16x32_bf16 v[30:33], v[58:61], v[188:191], v[30:33]
	v_mfma_f32_16x16x32_bf16 v[30:33], v[62:65], v[192:195], v[30:33]
	v_mfma_f32_16x16x32_bf16 v[26:29], v[66:69], v[188:191], v[26:29]
	v_mfma_f32_16x16x32_bf16 v[26:29], v[70:73], v[192:195], v[26:29]
	v_mfma_f32_16x16x32_bf16 v[14:17], v[58:61], v[202:205], v[14:17]
	v_mfma_f32_16x16x32_bf16 v[14:17], v[62:65], v[206:209], v[14:17]
	v_mfma_f32_16x16x32_bf16 v[10:13], v[66:69], v[202:205], v[10:13]
	v_mfma_f32_16x16x32_bf16 v[10:13], v[70:73], v[206:209], v[10:13]
	s_setprio 0
	s_setprio 1
	v_mfma_f32_16x16x32_bf16 v[54:57], v[138:141], v[162:165], v[54:57]
	v_mfma_f32_16x16x32_bf16 v[54:57], v[150:153], v[166:169], v[54:57]
	v_mfma_f32_16x16x32_bf16 v[50:53], v[154:157], v[162:165], v[50:53]
	v_mfma_f32_16x16x32_bf16 v[50:53], v[158:161], v[166:169], v[50:53]
	v_mfma_f32_16x16x32_bf16 v[38:41], v[138:141], v[180:183], v[38:41]
	v_mfma_f32_16x16x32_bf16 v[38:41], v[150:153], v[184:187], v[38:41]
	v_mfma_f32_16x16x32_bf16 v[34:37], v[154:157], v[180:183], v[34:37]
	v_mfma_f32_16x16x32_bf16 v[34:37], v[158:161], v[184:187], v[34:37]
	v_mfma_f32_16x16x32_bf16 v[22:25], v[138:141], v[188:191], v[22:25]
	v_mfma_f32_16x16x32_bf16 v[22:25], v[150:153], v[192:195], v[22:25]
	v_mfma_f32_16x16x32_bf16 v[18:21], v[154:157], v[188:191], v[18:21]
	v_mfma_f32_16x16x32_bf16 v[18:21], v[158:161], v[192:195], v[18:21]
	v_mfma_f32_16x16x32_bf16 v[6:9], v[138:141], v[202:205], v[6:9]
	v_mfma_f32_16x16x32_bf16 v[6:9], v[150:153], v[206:209], v[6:9]
	v_mfma_f32_16x16x32_bf16 v[2:5], v[154:157], v[202:205], v[2:5]
	v_mfma_f32_16x16x32_bf16 v[2:5], v[158:161], v[206:209], v[2:5]
	s_setprio 0
	s_barrier
	s_add_i32 s45, 0, 0x18000
	s_add_i32 s46, 0, 0x1c000
	v_add_u32_e32 v70, s45, v199
	v_add_u32_e32 v158, s46, v199
	ds_read_b128 v[58:61], v70
	ds_read_b128 v[62:65], v70 offset:1024
	ds_read_b128 v[66:69], v70 offset:2048
	ds_read_b128 v[70:73], v70 offset:3072
	ds_read_b128 v[138:141], v158
	ds_read_b128 v[150:153], v158 offset:1024
	ds_read_b128 v[154:157], v158 offset:2048
	ds_read_b128 v[158:161], v158 offset:3072
	s_add_u32 s2, s2, s12
	s_addc_u32 s3, s3, 0
	s_mov_b32 m0, s34
	v_lshl_add_u64 v[220:221], s[2:3], 0, v[174:175]
	ds_read_b128 v[162:165], v201 offset:32768
	ds_read_b128 v[166:169], v201 offset:33792
	ds_read_b128 v[180:183], v201 offset:34816
	ds_read_b128 v[184:187], v201 offset:35840
	ds_read_b128 v[188:191], v201 offset:36864
	ds_read_b128 v[192:195], v201 offset:37888
	ds_read_b128 v[202:205], v201 offset:38912
	ds_read_b128 v[206:209], v201 offset:39936
	global_load_lds_dwordx4 v[220:221], off
	v_lshl_add_u64 v[220:221], s[2:3], 0, v[172:173]
	s_mov_b32 m0, s35
	s_nop 0
	global_load_lds_dwordx4 v[220:221], off
	s_waitcnt vmcnt(8)
	s_waitcnt lgkmcnt(0)
	s_barrier
	s_setprio 1
	s_waitcnt lgkmcnt(0)
	v_mfma_f32_16x16x32_bf16 v[146:149], v[58:61], v[162:165], v[146:149]
	v_mfma_f32_16x16x32_bf16 v[146:149], v[62:65], v[166:169], v[146:149]
	v_mfma_f32_16x16x32_bf16 v[142:145], v[66:69], v[162:165], v[142:145]
	v_mfma_f32_16x16x32_bf16 v[142:145], v[70:73], v[166:169], v[142:145]
	v_mfma_f32_16x16x32_bf16 v[126:129], v[58:61], v[180:183], v[126:129]
	v_mfma_f32_16x16x32_bf16 v[126:129], v[62:65], v[184:187], v[126:129]
	v_mfma_f32_16x16x32_bf16 v[122:125], v[66:69], v[180:183], v[122:125]
	v_mfma_f32_16x16x32_bf16 v[122:125], v[70:73], v[184:187], v[122:125]
	v_mfma_f32_16x16x32_bf16 v[110:113], v[58:61], v[188:191], v[110:113]
	v_mfma_f32_16x16x32_bf16 v[110:113], v[62:65], v[192:195], v[110:113]
	v_mfma_f32_16x16x32_bf16 v[106:109], v[66:69], v[188:191], v[106:109]
	v_mfma_f32_16x16x32_bf16 v[106:109], v[70:73], v[192:195], v[106:109]
	v_mfma_f32_16x16x32_bf16 v[94:97], v[58:61], v[202:205], v[94:97]
	v_mfma_f32_16x16x32_bf16 v[94:97], v[62:65], v[206:209], v[94:97]
	v_mfma_f32_16x16x32_bf16 v[90:93], v[66:69], v[202:205], v[90:93]
	v_mfma_f32_16x16x32_bf16 v[90:93], v[70:73], v[206:209], v[90:93]
	s_setprio 0
	s_setprio 1
	v_mfma_f32_16x16x32_bf16 v[134:137], v[138:141], v[162:165], v[134:137]
	v_mfma_f32_16x16x32_bf16 v[134:137], v[150:153], v[166:169], v[134:137]
	v_mfma_f32_16x16x32_bf16 v[130:133], v[154:157], v[162:165], v[130:133]
	v_mfma_f32_16x16x32_bf16 v[130:133], v[158:161], v[166:169], v[130:133]
	v_mfma_f32_16x16x32_bf16 v[118:121], v[138:141], v[180:183], v[118:121]
	v_mfma_f32_16x16x32_bf16 v[118:121], v[150:153], v[184:187], v[118:121]
	v_mfma_f32_16x16x32_bf16 v[114:117], v[154:157], v[180:183], v[114:117]
	v_mfma_f32_16x16x32_bf16 v[114:117], v[158:161], v[184:187], v[114:117]
	v_mfma_f32_16x16x32_bf16 v[102:105], v[138:141], v[188:191], v[102:105]
	v_mfma_f32_16x16x32_bf16 v[102:105], v[150:153], v[192:195], v[102:105]
	v_mfma_f32_16x16x32_bf16 v[98:101], v[154:157], v[188:191], v[98:101]
	v_mfma_f32_16x16x32_bf16 v[98:101], v[158:161], v[192:195], v[98:101]
	v_mfma_f32_16x16x32_bf16 v[86:89], v[138:141], v[202:205], v[86:89]
	v_mfma_f32_16x16x32_bf16 v[86:89], v[150:153], v[206:209], v[86:89]
	v_mfma_f32_16x16x32_bf16 v[82:85], v[154:157], v[202:205], v[82:85]
	v_mfma_f32_16x16x32_bf16 v[82:85], v[158:161], v[206:209], v[82:85]
	s_setprio 0
	s_barrier
	s_add_i32 s2, s45, s29
	v_lshl_add_u64 v[196:197], v[196:197], 0, s[74:75]
	s_mov_b32 m0, s2
	ds_read_b128 v[162:165], v201 offset:49152
	ds_read_b128 v[166:169], v201 offset:50176
	ds_read_b128 v[180:183], v201 offset:51200
	ds_read_b128 v[184:187], v201 offset:52224
	ds_read_b128 v[188:191], v201 offset:53248
	ds_read_b128 v[192:195], v201 offset:54272
	ds_read_b128 v[202:205], v201 offset:55296
	ds_read_b128 v[206:209], v201 offset:56320
	global_load_lds_dwordx4 v[196:197], off
	v_lshl_add_u64 v[196:197], v[210:211], 0, s[74:75]
	s_add_i32 m0, s2, 0x2000
	s_add_i32 s2, s46, s29
	global_load_lds_dwordx4 v[196:197], off
	v_lshl_add_u64 v[196:197], v[212:213], 0, s[74:75]
	s_mov_b32 m0, s2
	s_nop 0
	global_load_lds_dwordx4 v[196:197], off
	v_lshl_add_u64 v[196:197], v[214:215], 0, s[74:75]
	s_add_i32 m0, s2, 0x2000
	s_nop 0
	global_load_lds_dwordx4 v[196:197], off
	v_lshl_add_u64 v[196:197], v[216:217], 0, s[74:75]
	s_mov_b32 m0, s38
	s_nop 0
	global_load_lds_dwordx4 v[196:197], off
	v_lshl_add_u64 v[196:197], v[218:219], 0, s[74:75]
	s_mov_b32 m0, s39
	s_nop 0
	global_load_lds_dwordx4 v[196:197], off
	s_waitcnt vmcnt(8)
	s_waitcnt lgkmcnt(0)
	s_barrier
	s_setprio 1
	s_waitcnt lgkmcnt(0)
	v_mfma_f32_16x16x32_bf16 v[78:81], v[58:61], v[162:165], v[78:81]
	v_mfma_f32_16x16x32_bf16 v[78:81], v[62:65], v[166:169], v[78:81]
	v_mfma_f32_16x16x32_bf16 v[74:77], v[66:69], v[162:165], v[74:77]
	v_mfma_f32_16x16x32_bf16 v[74:77], v[70:73], v[166:169], v[74:77]
	v_mfma_f32_16x16x32_bf16 v[46:49], v[58:61], v[180:183], v[46:49]
	v_mfma_f32_16x16x32_bf16 v[46:49], v[62:65], v[184:187], v[46:49]
	v_mfma_f32_16x16x32_bf16 v[42:45], v[66:69], v[180:183], v[42:45]
	v_mfma_f32_16x16x32_bf16 v[42:45], v[70:73], v[184:187], v[42:45]
	v_mfma_f32_16x16x32_bf16 v[30:33], v[58:61], v[188:191], v[30:33]
	v_mfma_f32_16x16x32_bf16 v[30:33], v[62:65], v[192:195], v[30:33]
	v_mfma_f32_16x16x32_bf16 v[26:29], v[66:69], v[188:191], v[26:29]
	v_mfma_f32_16x16x32_bf16 v[26:29], v[70:73], v[192:195], v[26:29]
	v_mfma_f32_16x16x32_bf16 v[14:17], v[58:61], v[202:205], v[14:17]
	v_mfma_f32_16x16x32_bf16 v[14:17], v[62:65], v[206:209], v[14:17]
	v_mfma_f32_16x16x32_bf16 v[10:13], v[66:69], v[202:205], v[10:13]
	v_mfma_f32_16x16x32_bf16 v[10:13], v[70:73], v[206:209], v[10:13]
	s_setprio 0
	s_setprio 1
	v_mfma_f32_16x16x32_bf16 v[54:57], v[138:141], v[162:165], v[54:57]
	v_mfma_f32_16x16x32_bf16 v[54:57], v[150:153], v[166:169], v[54:57]
	v_mfma_f32_16x16x32_bf16 v[50:53], v[154:157], v[162:165], v[50:53]
	v_mfma_f32_16x16x32_bf16 v[50:53], v[158:161], v[166:169], v[50:53]
	v_mfma_f32_16x16x32_bf16 v[38:41], v[138:141], v[180:183], v[38:41]
	v_mfma_f32_16x16x32_bf16 v[38:41], v[150:153], v[184:187], v[38:41]
	v_mfma_f32_16x16x32_bf16 v[34:37], v[154:157], v[180:183], v[34:37]
	v_mfma_f32_16x16x32_bf16 v[34:37], v[158:161], v[184:187], v[34:37]
	v_mfma_f32_16x16x32_bf16 v[22:25], v[138:141], v[188:191], v[22:25]
	v_mfma_f32_16x16x32_bf16 v[22:25], v[150:153], v[192:195], v[22:25]
	v_mfma_f32_16x16x32_bf16 v[18:21], v[154:157], v[188:191], v[18:21]
	v_mfma_f32_16x16x32_bf16 v[18:21], v[158:161], v[192:195], v[18:21]
	v_mfma_f32_16x16x32_bf16 v[6:9], v[138:141], v[202:205], v[6:9]
	v_mfma_f32_16x16x32_bf16 v[6:9], v[150:153], v[206:209], v[6:9]
	v_mfma_f32_16x16x32_bf16 v[2:5], v[154:157], v[202:205], v[2:5]
	v_mfma_f32_16x16x32_bf16 v[2:5], v[158:161], v[206:209], v[2:5]
	s_setprio 0
	s_barrier
	s_add_u32 s4, s4, 0x100
	s_addc_u32 s5, s5, 0
	s_add_u32 s26, s26, 0x100
	s_addc_u32 s27, s27, 0
	s_cmp_ge_u32 s33, s37
	s_mov_b32 s2, s33
	s_cbranch_scc0 .LBB0_557
	s_and_b64 vcc, exec, s[18:19]
	s_cbranch_vccz .LBB0_560
	s_barrier

.LBB0_597:
	s_ashr_i32 s9, s8, 31
	s_lshl_b64 s[12:13], s[8:9], 19
	s_add_u32 s12, s82, s12
	s_addc_u32 s13, s83, s13
	s_and_b64 s[14:15], s[0:1], exec
	s_cselect_b32 s9, s13, s17
	s_cselect_b32 s34, s12, s16
	s_ashr_i32 s11, s10, 31
	s_lshl_b64 s[14:15], s[10:11], 19
	s_add_u32 s14, s20, s14
	s_addc_u32 s15, s21, s15
	s_and_b64 s[18:19], s[0:1], exec
	s_cselect_b32 s11, s15, s3
	s_cselect_b32 s35, s14, s2
	s_add_u32 s16, s16, 0x40080
	s_addc_u32 s17, s17, 0
	s_add_u32 s33, s2, 0x100
	s_addc_u32 s36, s3, 0
	s_mov_b32 s37, -2
	s_add_u32 s2, s16, 0xfffc0080
	s_addc_u32 s3, s17, -1
	s_add_i32 s38, 0, 0x10000
	s_cmp_eq_u32 s37, 12
	s_cselect_b32 s19, s9, s3
	s_cselect_b32 s18, s34, s2
	s_cselect_b32 s3, s11, s36
	s_cselect_b32 s2, s35, s33
	s_add_i32 s40, 0, 0x14000
	v_add_u32_e32 v154, s38, v159
	v_add_u32_e32 v174, s40, v159
	ds_read_b128 v[142:145], v154
	ds_read_b128 v[146:149], v154 offset:1024
	ds_read_b128 v[150:153], v154 offset:2048
	ds_read_b128 v[154:157], v154 offset:3072
	ds_read_b128 v[162:165], v174
	ds_read_b128 v[166:169], v174 offset:1024
	ds_read_b128 v[170:173], v174 offset:2048
	ds_read_b128 v[174:177], v174 offset:3072
	v_lshl_add_u64 v[210:211], s[16:17], 0, v[138:139]
	s_add_i32 m0, s23, 0xc000
	ds_read_b128 v[178:181], v161
	ds_read_b128 v[182:185], v161 offset:1024
	ds_read_b128 v[186:189], v161 offset:2048
	ds_read_b128 v[190:193], v161 offset:3072
	ds_read_b128 v[194:197], v161 offset:4096
	ds_read_b128 v[198:201], v161 offset:5120
	ds_read_b128 v[202:205], v161 offset:6144
	ds_read_b128 v[206:209], v161 offset:7168
	global_load_lds_dwordx4 v[210:211], off
	v_lshl_add_u64 v[210:211], s[16:17], 0, v[140:141]
	s_add_i32 m0, s23, 0xe000
	s_nop 0
	global_load_lds_dwordx4 v[210:211], off
	s_waitcnt vmcnt(8)
	s_waitcnt lgkmcnt(0)
	s_barrier
	s_setprio 1
	s_waitcnt lgkmcnt(0)
	v_mfma_f32_16x16x32_bf16 v[126:129], v[142:145], v[178:181], 0
	v_mfma_f32_16x16x32_bf16 v[126:129], v[146:149], v[182:185], v[126:129]
	v_mfma_f32_16x16x32_bf16 v[118:121], v[150:153], v[178:181], 0
	v_mfma_f32_16x16x32_bf16 v[118:121], v[154:157], v[182:185], v[118:121]
	v_mfma_f32_16x16x32_bf16 v[110:113], v[142:145], v[186:189], 0
	v_mfma_f32_16x16x32_bf16 v[110:113], v[146:149], v[190:193], v[110:113]
	v_mfma_f32_16x16x32_bf16 v[102:105], v[150:153], v[186:189], 0
	v_mfma_f32_16x16x32_bf16 v[102:105], v[154:157], v[190:193], v[102:105]
	v_mfma_f32_16x16x32_bf16 v[94:97], v[142:145], v[194:197], 0
	v_mfma_f32_16x16x32_bf16 v[94:97], v[146:149], v[198:201], v[94:97]
	v_mfma_f32_16x16x32_bf16 v[86:89], v[150:153], v[194:197], 0
	v_mfma_f32_16x16x32_bf16 v[86:89], v[154:157], v[198:201], v[86:89]
	v_mfma_f32_16x16x32_bf16 v[78:81], v[142:145], v[202:205], 0
	v_mfma_f32_16x16x32_bf16 v[78:81], v[146:149], v[206:209], v[78:81]
	v_mfma_f32_16x16x32_bf16 v[70:73], v[150:153], v[202:205], 0
	v_mfma_f32_16x16x32_bf16 v[70:73], v[154:157], v[206:209], v[70:73]
	s_setprio 0
	s_setprio 1
	v_mfma_f32_16x16x32_bf16 v[122:125], v[162:165], v[178:181], 0
	v_mfma_f32_16x16x32_bf16 v[122:125], v[166:169], v[182:185], v[122:125]
	v_mfma_f32_16x16x32_bf16 v[114:117], v[170:173], v[178:181], 0
	v_mfma_f32_16x16x32_bf16 v[114:117], v[174:177], v[182:185], v[114:117]
	v_mfma_f32_16x16x32_bf16 v[106:109], v[162:165], v[186:189], 0
	v_mfma_f32_16x16x32_bf16 v[106:109], v[166:169], v[190:193], v[106:109]
	v_mfma_f32_16x16x32_bf16 v[98:101], v[170:173], v[186:189], 0
	v_mfma_f32_16x16x32_bf16 v[98:101], v[174:177], v[190:193], v[98:101]
	v_mfma_f32_16x16x32_bf16 v[90:93], v[162:165], v[194:197], 0
	v_mfma_f32_16x16x32_bf16 v[90:93], v[166:169], v[198:201], v[90:93]
	v_mfma_f32_16x16x32_bf16 v[82:85], v[170:173], v[194:197], 0
	v_mfma_f32_16x16x32_bf16 v[82:85], v[174:177], v[198:201], v[82:85]
	v_mfma_f32_16x16x32_bf16 v[74:77], v[162:165], v[202:205], 0
	v_mfma_f32_16x16x32_bf16 v[74:77], v[166:169], v[206:209], v[74:77]
	v_mfma_f32_16x16x32_bf16 v[66:69], v[170:173], v[202:205], 0
	v_mfma_f32_16x16x32_bf16 v[66:69], v[174:177], v[206:209], v[66:69]
	s_setprio 0
	s_barrier
	s_add_i32 s38, s38, s22
	v_lshl_add_u64 v[210:211], s[2:3], 0, v[0:1]
	s_mov_b32 m0, s38
	ds_read_b128 v[178:181], v161 offset:16384
	ds_read_b128 v[182:185], v161 offset:17408
	ds_read_b128 v[186:189], v161 offset:18432
	ds_read_b128 v[190:193], v161 offset:19456
	ds_read_b128 v[194:197], v161 offset:20480
	ds_read_b128 v[198:201], v161 offset:21504
	ds_read_b128 v[202:205], v161 offset:22528
	ds_read_b128 v[206:209], v161 offset:23552
	global_load_lds_dwordx4 v[210:211], off
	s_add_i32 m0, s38, 0x2000
	s_add_u32 s38, s2, 0x40000
	v_lshl_add_u64 v[212:213], s[2:3], 0, v[130:131]
	s_addc_u32 s39, s3, 0
	s_add_i32 s40, s40, s22
	global_load_lds_dwordx4 v[212:213], off
	v_lshl_add_u64 v[214:215], s[38:39], 0, v[0:1]
	s_mov_b32 m0, s40
	v_lshl_add_u64 v[216:217], s[18:19], 0, v[132:133]
	global_load_lds_dwordx4 v[214:215], off
	v_lshl_add_u64 v[214:215], s[38:39], 0, v[130:131]
	s_add_i32 m0, s40, 0x2000
	s_nop 0
	global_load_lds_dwordx4 v[214:215], off
	v_lshl_add_u64 v[214:215], s[18:19], 0, v[134:135]
	s_mov_b32 m0, s23
	s_nop 0
	global_load_lds_dwordx4 v[214:215], off
	s_mov_b32 m0, s24
	s_nop 0
	global_load_lds_dwordx4 v[216:217], off
	s_waitcnt vmcnt(8)
	s_waitcnt lgkmcnt(0)
	s_barrier
	s_setprio 1
	s_waitcnt lgkmcnt(0)
	v_mfma_f32_16x16x32_bf16 v[62:65], v[142:145], v[178:181], 0
	v_mfma_f32_16x16x32_bf16 v[62:65], v[146:149], v[182:185], v[62:65]
	v_mfma_f32_16x16x32_bf16 v[54:57], v[150:153], v[178:181], 0
	v_mfma_f32_16x16x32_bf16 v[54:57], v[154:157], v[182:185], v[54:57]
	v_mfma_f32_16x16x32_bf16 v[46:49], v[142:145], v[186:189], 0
	v_mfma_f32_16x16x32_bf16 v[46:49], v[146:149], v[190:193], v[46:49]
	v_mfma_f32_16x16x32_bf16 v[38:41], v[150:153], v[186:189], 0
	v_mfma_f32_16x16x32_bf16 v[38:41], v[154:157], v[190:193], v[38:41]
	v_mfma_f32_16x16x32_bf16 v[30:33], v[142:145], v[194:197], 0
	v_mfma_f32_16x16x32_bf16 v[30:33], v[146:149], v[198:201], v[30:33]
	v_mfma_f32_16x16x32_bf16 v[22:25], v[150:153], v[194:197], 0
	v_mfma_f32_16x16x32_bf16 v[22:25], v[154:157], v[198:201], v[22:25]
	v_mfma_f32_16x16x32_bf16 v[14:17], v[142:145], v[202:205], 0
	v_mfma_f32_16x16x32_bf16 v[14:17], v[146:149], v[206:209], v[14:17]
	v_mfma_f32_16x16x32_bf16 v[6:9], v[150:153], v[202:205], 0
	v_mfma_f32_16x16x32_bf16 v[6:9], v[154:157], v[206:209], v[6:9]
	s_setprio 0
	s_setprio 1
	v_mfma_f32_16x16x32_bf16 v[58:61], v[162:165], v[178:181], 0
	v_mfma_f32_16x16x32_bf16 v[58:61], v[166:169], v[182:185], v[58:61]
	v_mfma_f32_16x16x32_bf16 v[50:53], v[170:173], v[178:181], 0
	v_mfma_f32_16x16x32_bf16 v[50:53], v[174:177], v[182:185], v[50:53]
	v_mfma_f32_16x16x32_bf16 v[42:45], v[162:165], v[186:189], 0
	v_mfma_f32_16x16x32_bf16 v[42:45], v[166:169], v[190:193], v[42:45]
	v_mfma_f32_16x16x32_bf16 v[34:37], v[170:173], v[186:189], 0
	v_mfma_f32_16x16x32_bf16 v[34:37], v[174:177], v[190:193], v[34:37]
	v_mfma_f32_16x16x32_bf16 v[26:29], v[162:165], v[194:197], 0
	v_mfma_f32_16x16x32_bf16 v[26:29], v[166:169], v[198:201], v[26:29]
	v_mfma_f32_16x16x32_bf16 v[18:21], v[170:173], v[194:197], 0
	v_mfma_f32_16x16x32_bf16 v[18:21], v[174:177], v[198:201], v[18:21]
	v_mfma_f32_16x16x32_bf16 v[10:13], v[162:165], v[202:205], 0
	v_mfma_f32_16x16x32_bf16 v[10:13], v[166:169], v[206:209], v[10:13]
	v_mfma_f32_16x16x32_bf16 v[2:5], v[170:173], v[202:205], 0
	v_mfma_f32_16x16x32_bf16 v[2:5], v[174:177], v[206:209], v[2:5]
	s_setprio 0
	s_barrier
	s_add_i32 s38, 0, 0x18000
	s_add_i32 s39, 0, 0x1c000
	v_add_u32_e32 v154, s38, v159
	v_add_u32_e32 v174, s39, v159
	ds_read_b128 v[142:145], v154
	ds_read_b128 v[146:149], v154 offset:1024
	ds_read_b128 v[150:153], v154 offset:2048
	ds_read_b128 v[154:157], v154 offset:3072
	ds_read_b128 v[162:165], v174
	ds_read_b128 v[166:169], v174 offset:1024
	ds_read_b128 v[170:173], v174 offset:2048
	ds_read_b128 v[174:177], v174 offset:3072
	s_add_u32 s18, s18, 0x40000
	s_addc_u32 s19, s19, 0
	s_mov_b32 m0, s25
	v_lshl_add_u64 v[218:219], s[18:19], 0, v[134:135]
	ds_read_b128 v[178:181], v161 offset:32768
	ds_read_b128 v[182:185], v161 offset:33792
	ds_read_b128 v[186:189], v161 offset:34816
	ds_read_b128 v[190:193], v161 offset:35840
	ds_read_b128 v[194:197], v161 offset:36864
	ds_read_b128 v[198:201], v161 offset:37888
	ds_read_b128 v[202:205], v161 offset:38912
	ds_read_b128 v[206:209], v161 offset:39936
	global_load_lds_dwordx4 v[218:219], off
	v_lshl_add_u64 v[218:219], s[18:19], 0, v[132:133]
	s_mov_b32 m0, s26
	s_nop 0
	global_load_lds_dwordx4 v[218:219], off
	s_waitcnt vmcnt(8)
	s_waitcnt lgkmcnt(0)
	s_barrier
	s_setprio 1
	s_waitcnt lgkmcnt(0)
	v_mfma_f32_16x16x32_bf16 v[126:129], v[142:145], v[178:181], v[126:129]
	v_mfma_f32_16x16x32_bf16 v[126:129], v[146:149], v[182:185], v[126:129]
	v_mfma_f32_16x16x32_bf16 v[118:121], v[150:153], v[178:181], v[118:121]
	v_mfma_f32_16x16x32_bf16 v[118:121], v[154:157], v[182:185], v[118:121]
	v_mfma_f32_16x16x32_bf16 v[110:113], v[142:145], v[186:189], v[110:113]
	v_mfma_f32_16x16x32_bf16 v[110:113], v[146:149], v[190:193], v[110:113]
	v_mfma_f32_16x16x32_bf16 v[102:105], v[150:153], v[186:189], v[102:105]
	v_mfma_f32_16x16x32_bf16 v[102:105], v[154:157], v[190:193], v[102:105]
	v_mfma_f32_16x16x32_bf16 v[94:97], v[142:145], v[194:197], v[94:97]
	v_mfma_f32_16x16x32_bf16 v[94:97], v[146:149], v[198:201], v[94:97]
	v_mfma_f32_16x16x32_bf16 v[86:89], v[150:153], v[194:197], v[86:89]
	v_mfma_f32_16x16x32_bf16 v[86:89], v[154:157], v[198:201], v[86:89]
	v_mfma_f32_16x16x32_bf16 v[78:81], v[142:145], v[202:205], v[78:81]
	v_mfma_f32_16x16x32_bf16 v[78:81], v[146:149], v[206:209], v[78:81]
	v_mfma_f32_16x16x32_bf16 v[70:73], v[150:153], v[202:205], v[70:73]
	v_mfma_f32_16x16x32_bf16 v[70:73], v[154:157], v[206:209], v[70:73]
	s_setprio 0
	s_setprio 1
	v_mfma_f32_16x16x32_bf16 v[122:125], v[162:165], v[178:181], v[122:125]
	v_mfma_f32_16x16x32_bf16 v[122:125], v[166:169], v[182:185], v[122:125]
	v_mfma_f32_16x16x32_bf16 v[114:117], v[170:173], v[178:181], v[114:117]
	v_mfma_f32_16x16x32_bf16 v[114:117], v[174:177], v[182:185], v[114:117]
	v_mfma_f32_16x16x32_bf16 v[106:109], v[162:165], v[186:189], v[106:109]
	v_mfma_f32_16x16x32_bf16 v[106:109], v[166:169], v[190:193], v[106:109]
	v_mfma_f32_16x16x32_bf16 v[98:101], v[170:173], v[186:189], v[98:101]
	v_mfma_f32_16x16x32_bf16 v[98:101], v[174:177], v[190:193], v[98:101]
	v_mfma_f32_16x16x32_bf16 v[90:93], v[162:165], v[194:197], v[90:93]
	v_mfma_f32_16x16x32_bf16 v[90:93], v[166:169], v[198:201], v[90:93]
	v_mfma_f32_16x16x32_bf16 v[82:85], v[170:173], v[194:197], v[82:85]
	v_mfma_f32_16x16x32_bf16 v[82:85], v[174:177], v[198:201], v[82:85]
	v_mfma_f32_16x16x32_bf16 v[74:77], v[162:165], v[202:205], v[74:77]
	v_mfma_f32_16x16x32_bf16 v[74:77], v[166:169], v[206:209], v[74:77]
	v_mfma_f32_16x16x32_bf16 v[66:69], v[170:173], v[202:205], v[66:69]
	v_mfma_f32_16x16x32_bf16 v[66:69], v[174:177], v[206:209], v[66:69]
	s_setprio 0
	s_barrier
	s_add_i32 s18, s38, s22
	v_lshl_add_u64 v[210:211], v[210:211], 0, s[74:75]
	s_mov_b32 m0, s18
	ds_read_b128 v[178:181], v161 offset:49152
	ds_read_b128 v[182:185], v161 offset:50176
	ds_read_b128 v[186:189], v161 offset:51200
	ds_read_b128 v[190:193], v161 offset:52224
	ds_read_b128 v[194:197], v161 offset:53248
	ds_read_b128 v[198:201], v161 offset:54272
	ds_read_b128 v[202:205], v161 offset:55296
	ds_read_b128 v[206:209], v161 offset:56320
	global_load_lds_dwordx4 v[210:211], off
	s_add_i32 m0, s18, 0x2000
	s_add_u32 s2, s2, 0x40080
	v_lshl_add_u64 v[210:211], v[212:213], 0, s[74:75]
	s_addc_u32 s3, s3, 0
	s_add_i32 s18, s39, s22
	global_load_lds_dwordx4 v[210:211], off
	v_lshl_add_u64 v[210:211], s[2:3], 0, v[0:1]
	s_mov_b32 m0, s18
	s_nop 0
	global_load_lds_dwordx4 v[210:211], off
	v_lshl_add_u64 v[210:211], s[2:3], 0, v[130:131]
	s_add_i32 m0, s18, 0x2000
	s_nop 0
	global_load_lds_dwordx4 v[210:211], off
	v_lshl_add_u64 v[210:211], v[214:215], 0, s[74:75]
	s_mov_b32 m0, s27
	s_nop 0
	global_load_lds_dwordx4 v[210:211], off
	v_lshl_add_u64 v[210:211], v[216:217], 0, s[74:75]
	s_mov_b32 m0, s28
	s_nop 0
	global_load_lds_dwordx4 v[210:211], off
	s_waitcnt vmcnt(8)
	s_waitcnt lgkmcnt(0)
	s_barrier
	s_setprio 1
	s_waitcnt lgkmcnt(0)
	v_mfma_f32_16x16x32_bf16 v[62:65], v[142:145], v[178:181], v[62:65]
	v_mfma_f32_16x16x32_bf16 v[62:65], v[146:149], v[182:185], v[62:65]
	v_mfma_f32_16x16x32_bf16 v[54:57], v[150:153], v[178:181], v[54:57]
	v_mfma_f32_16x16x32_bf16 v[54:57], v[154:157], v[182:185], v[54:57]
	v_mfma_f32_16x16x32_bf16 v[46:49], v[142:145], v[186:189], v[46:49]
	v_mfma_f32_16x16x32_bf16 v[46:49], v[146:149], v[190:193], v[46:49]
	v_mfma_f32_16x16x32_bf16 v[38:41], v[150:153], v[186:189], v[38:41]
	v_mfma_f32_16x16x32_bf16 v[38:41], v[154:157], v[190:193], v[38:41]
	v_mfma_f32_16x16x32_bf16 v[30:33], v[142:145], v[194:197], v[30:33]
	v_mfma_f32_16x16x32_bf16 v[30:33], v[146:149], v[198:201], v[30:33]
	v_mfma_f32_16x16x32_bf16 v[22:25], v[150:153], v[194:197], v[22:25]
	v_mfma_f32_16x16x32_bf16 v[22:25], v[154:157], v[198:201], v[22:25]
	v_mfma_f32_16x16x32_bf16 v[14:17], v[142:145], v[202:205], v[14:17]
	v_mfma_f32_16x16x32_bf16 v[14:17], v[146:149], v[206:209], v[14:17]
	v_mfma_f32_16x16x32_bf16 v[6:9], v[150:153], v[202:205], v[6:9]
	v_mfma_f32_16x16x32_bf16 v[6:9], v[154:157], v[206:209], v[6:9]
	s_setprio 0
	s_setprio 1
	v_mfma_f32_16x16x32_bf16 v[58:61], v[162:165], v[178:181], v[58:61]
	v_mfma_f32_16x16x32_bf16 v[58:61], v[166:169], v[182:185], v[58:61]
	v_mfma_f32_16x16x32_bf16 v[50:53], v[170:173], v[178:181], v[50:53]
	v_mfma_f32_16x16x32_bf16 v[50:53], v[174:177], v[182:185], v[50:53]
	v_mfma_f32_16x16x32_bf16 v[42:45], v[162:165], v[186:189], v[42:45]
	v_mfma_f32_16x16x32_bf16 v[42:45], v[166:169], v[190:193], v[42:45]
	v_mfma_f32_16x16x32_bf16 v[34:37], v[170:173], v[186:189], v[34:37]
	v_mfma_f32_16x16x32_bf16 v[34:37], v[174:177], v[190:193], v[34:37]
	v_mfma_f32_16x16x32_bf16 v[26:29], v[162:165], v[194:197], v[26:29]
	v_mfma_f32_16x16x32_bf16 v[26:29], v[166:169], v[198:201], v[26:29]
	v_mfma_f32_16x16x32_bf16 v[18:21], v[170:173], v[194:197], v[18:21]
	v_mfma_f32_16x16x32_bf16 v[18:21], v[174:177], v[198:201], v[18:21]
	v_mfma_f32_16x16x32_bf16 v[10:13], v[162:165], v[202:205], v[10:13]
	v_mfma_f32_16x16x32_bf16 v[10:13], v[166:169], v[206:209], v[10:13]
	v_mfma_f32_16x16x32_bf16 v[2:5], v[170:173], v[202:205], v[2:5]
	v_mfma_f32_16x16x32_bf16 v[2:5], v[174:177], v[206:209], v[2:5]
	s_setprio 0
	s_barrier
	s_add_i32 s37, s37, 2
	s_add_u32 s16, s16, 0x100
	s_addc_u32 s17, s17, 0
	s_add_u32 s33, s33, 0x100
	s_addc_u32 s36, s36, 0
	s_cmp_gt_u32 s37, 13
.LBB0_598:
	s_add_u32 s2, s16, 0xfffc0080
	s_addc_u32 s3, s17, -1
	s_add_i32 s38, 0, 0x10000
	s_cmp_eq_u32 s37, 12
	s_cselect_b32 s19, s9, s3
	s_cselect_b32 s18, s34, s2
	s_cselect_b32 s3, s11, s36
	s_cselect_b32 s2, s35, s33
	s_add_i32 s40, 0, 0x14000
	v_add_u32_e32 v154, s38, v159
	v_add_u32_e32 v174, s40, v159
	ds_read_b128 v[142:145], v154
	ds_read_b128 v[146:149], v154 offset:1024
	ds_read_b128 v[150:153], v154 offset:2048
	ds_read_b128 v[154:157], v154 offset:3072
	ds_read_b128 v[162:165], v174
	ds_read_b128 v[166:169], v174 offset:1024
	ds_read_b128 v[170:173], v174 offset:2048
	ds_read_b128 v[174:177], v174 offset:3072
	v_lshl_add_u64 v[210:211], s[16:17], 0, v[138:139]
	s_add_i32 m0, s23, 0xc000
	ds_read_b128 v[178:181], v161
	ds_read_b128 v[182:185], v161 offset:1024
	ds_read_b128 v[186:189], v161 offset:2048
	ds_read_b128 v[190:193], v161 offset:3072
	ds_read_b128 v[194:197], v161 offset:4096
	ds_read_b128 v[198:201], v161 offset:5120
	ds_read_b128 v[202:205], v161 offset:6144
	ds_read_b128 v[206:209], v161 offset:7168
	global_load_lds_dwordx4 v[210:211], off
	v_lshl_add_u64 v[210:211], s[16:17], 0, v[140:141]
	s_add_i32 m0, s23, 0xe000
	s_nop 0
	global_load_lds_dwordx4 v[210:211], off
	s_waitcnt vmcnt(8)
	s_waitcnt lgkmcnt(0)
	s_barrier
	s_setprio 1
	s_waitcnt lgkmcnt(0)
	v_mfma_f32_16x16x32_bf16 v[126:129], v[142:145], v[178:181], v[126:129]
	v_mfma_f32_16x16x32_bf16 v[126:129], v[146:149], v[182:185], v[126:129]
	v_mfma_f32_16x16x32_bf16 v[118:121], v[150:153], v[178:181], v[118:121]
	v_mfma_f32_16x16x32_bf16 v[118:121], v[154:157], v[182:185], v[118:121]
	v_mfma_f32_16x16x32_bf16 v[110:113], v[142:145], v[186:189], v[110:113]
	v_mfma_f32_16x16x32_bf16 v[110:113], v[146:149], v[190:193], v[110:113]
	v_mfma_f32_16x16x32_bf16 v[102:105], v[150:153], v[186:189], v[102:105]
	v_mfma_f32_16x16x32_bf16 v[102:105], v[154:157], v[190:193], v[102:105]
	v_mfma_f32_16x16x32_bf16 v[94:97], v[142:145], v[194:197], v[94:97]
	v_mfma_f32_16x16x32_bf16 v[94:97], v[146:149], v[198:201], v[94:97]
	v_mfma_f32_16x16x32_bf16 v[86:89], v[150:153], v[194:197], v[86:89]
	v_mfma_f32_16x16x32_bf16 v[86:89], v[154:157], v[198:201], v[86:89]
	v_mfma_f32_16x16x32_bf16 v[78:81], v[142:145], v[202:205], v[78:81]
	v_mfma_f32_16x16x32_bf16 v[78:81], v[146:149], v[206:209], v[78:81]
	v_mfma_f32_16x16x32_bf16 v[70:73], v[150:153], v[202:205], v[70:73]
	v_mfma_f32_16x16x32_bf16 v[70:73], v[154:157], v[206:209], v[70:73]
	s_setprio 0
	s_setprio 1
	v_mfma_f32_16x16x32_bf16 v[122:125], v[162:165], v[178:181], v[122:125]
	v_mfma_f32_16x16x32_bf16 v[122:125], v[166:169], v[182:185], v[122:125]
	v_mfma_f32_16x16x32_bf16 v[114:117], v[170:173], v[178:181], v[114:117]
	v_mfma_f32_16x16x32_bf16 v[114:117], v[174:177], v[182:185], v[114:117]
	v_mfma_f32_16x16x32_bf16 v[106:109], v[162:165], v[186:189], v[106:109]
	v_mfma_f32_16x16x32_bf16 v[106:109], v[166:169], v[190:193], v[106:109]
	v_mfma_f32_16x16x32_bf16 v[98:101], v[170:173], v[186:189], v[98:101]
	v_mfma_f32_16x16x32_bf16 v[98:101], v[174:177], v[190:193], v[98:101]
	v_mfma_f32_16x16x32_bf16 v[90:93], v[162:165], v[194:197], v[90:93]
	v_mfma_f32_16x16x32_bf16 v[90:93], v[166:169], v[198:201], v[90:93]
	v_mfma_f32_16x16x32_bf16 v[82:85], v[170:173], v[194:197], v[82:85]
	v_mfma_f32_16x16x32_bf16 v[82:85], v[174:177], v[198:201], v[82:85]
	v_mfma_f32_16x16x32_bf16 v[74:77], v[162:165], v[202:205], v[74:77]
	v_mfma_f32_16x16x32_bf16 v[74:77], v[166:169], v[206:209], v[74:77]
	v_mfma_f32_16x16x32_bf16 v[66:69], v[170:173], v[202:205], v[66:69]
	v_mfma_f32_16x16x32_bf16 v[66:69], v[174:177], v[206:209], v[66:69]
	s_setprio 0
	s_barrier
	s_add_i32 s38, s38, s22
	v_lshl_add_u64 v[210:211], s[2:3], 0, v[0:1]
	s_mov_b32 m0, s38
	ds_read_b128 v[178:181], v161 offset:16384
	ds_read_b128 v[182:185], v161 offset:17408
	ds_read_b128 v[186:189], v161 offset:18432
	ds_read_b128 v[190:193], v161 offset:19456
	ds_read_b128 v[194:197], v161 offset:20480
	ds_read_b128 v[198:201], v161 offset:21504
	ds_read_b128 v[202:205], v161 offset:22528
	ds_read_b128 v[206:209], v161 offset:23552
	global_load_lds_dwordx4 v[210:211], off
	s_add_i32 m0, s38, 0x2000
	s_add_u32 s38, s2, 0x40000
	v_lshl_add_u64 v[212:213], s[2:3], 0, v[130:131]
	s_addc_u32 s39, s3, 0
	s_add_i32 s40, s40, s22
	global_load_lds_dwordx4 v[212:213], off
	v_lshl_add_u64 v[214:215], s[38:39], 0, v[0:1]
	s_mov_b32 m0, s40
	v_lshl_add_u64 v[216:217], s[18:19], 0, v[132:133]
	global_load_lds_dwordx4 v[214:215], off
	v_lshl_add_u64 v[214:215], s[38:39], 0, v[130:131]
	s_add_i32 m0, s40, 0x2000
	s_nop 0
	global_load_lds_dwordx4 v[214:215], off
	v_lshl_add_u64 v[214:215], s[18:19], 0, v[134:135]
	s_mov_b32 m0, s23
	s_nop 0
	global_load_lds_dwordx4 v[214:215], off
	s_mov_b32 m0, s24
	s_nop 0
	global_load_lds_dwordx4 v[216:217], off
	s_waitcnt vmcnt(8)
	s_waitcnt lgkmcnt(0)
	s_barrier
	s_setprio 1
	s_waitcnt lgkmcnt(0)
	v_mfma_f32_16x16x32_bf16 v[62:65], v[142:145], v[178:181], v[62:65]
	v_mfma_f32_16x16x32_bf16 v[62:65], v[146:149], v[182:185], v[62:65]
	v_mfma_f32_16x16x32_bf16 v[54:57], v[150:153], v[178:181], v[54:57]
	v_mfma_f32_16x16x32_bf16 v[54:57], v[154:157], v[182:185], v[54:57]
	v_mfma_f32_16x16x32_bf16 v[46:49], v[142:145], v[186:189], v[46:49]
	v_mfma_f32_16x16x32_bf16 v[46:49], v[146:149], v[190:193], v[46:49]
	v_mfma_f32_16x16x32_bf16 v[38:41], v[150:153], v[186:189], v[38:41]
	v_mfma_f32_16x16x32_bf16 v[38:41], v[154:157], v[190:193], v[38:41]
	v_mfma_f32_16x16x32_bf16 v[30:33], v[142:145], v[194:197], v[30:33]
	v_mfma_f32_16x16x32_bf16 v[30:33], v[146:149], v[198:201], v[30:33]
	v_mfma_f32_16x16x32_bf16 v[22:25], v[150:153], v[194:197], v[22:25]
	v_mfma_f32_16x16x32_bf16 v[22:25], v[154:157], v[198:201], v[22:25]
	v_mfma_f32_16x16x32_bf16 v[14:17], v[142:145], v[202:205], v[14:17]
	v_mfma_f32_16x16x32_bf16 v[14:17], v[146:149], v[206:209], v[14:17]
	v_mfma_f32_16x16x32_bf16 v[6:9], v[150:153], v[202:205], v[6:9]
	v_mfma_f32_16x16x32_bf16 v[6:9], v[154:157], v[206:209], v[6:9]
	s_setprio 0
	s_setprio 1
	v_mfma_f32_16x16x32_bf16 v[58:61], v[162:165], v[178:181], v[58:61]
	v_mfma_f32_16x16x32_bf16 v[58:61], v[166:169], v[182:185], v[58:61]
	v_mfma_f32_16x16x32_bf16 v[50:53], v[170:173], v[178:181], v[50:53]
	v_mfma_f32_16x16x32_bf16 v[50:53], v[174:177], v[182:185], v[50:53]
	v_mfma_f32_16x16x32_bf16 v[42:45], v[162:165], v[186:189], v[42:45]
	v_mfma_f32_16x16x32_bf16 v[42:45], v[166:169], v[190:193], v[42:45]
	v_mfma_f32_16x16x32_bf16 v[34:37], v[170:173], v[186:189], v[34:37]
	v_mfma_f32_16x16x32_bf16 v[34:37], v[174:177], v[190:193], v[34:37]
	v_mfma_f32_16x16x32_bf16 v[26:29], v[162:165], v[194:197], v[26:29]
	v_mfma_f32_16x16x32_bf16 v[26:29], v[166:169], v[198:201], v[26:29]
	v_mfma_f32_16x16x32_bf16 v[18:21], v[170:173], v[194:197], v[18:21]
	v_mfma_f32_16x16x32_bf16 v[18:21], v[174:177], v[198:201], v[18:21]
	v_mfma_f32_16x16x32_bf16 v[10:13], v[162:165], v[202:205], v[10:13]
	v_mfma_f32_16x16x32_bf16 v[10:13], v[166:169], v[206:209], v[10:13]
	v_mfma_f32_16x16x32_bf16 v[2:5], v[170:173], v[202:205], v[2:5]
	v_mfma_f32_16x16x32_bf16 v[2:5], v[174:177], v[206:209], v[2:5]
	s_setprio 0
	s_barrier
	s_add_i32 s38, 0, 0x18000
	s_add_i32 s39, 0, 0x1c000
	v_add_u32_e32 v154, s38, v159
	v_add_u32_e32 v174, s39, v159
	ds_read_b128 v[142:145], v154
	ds_read_b128 v[146:149], v154 offset:1024
	ds_read_b128 v[150:153], v154 offset:2048
	ds_read_b128 v[154:157], v154 offset:3072
	ds_read_b128 v[162:165], v174
	ds_read_b128 v[166:169], v174 offset:1024
	ds_read_b128 v[170:173], v174 offset:2048
	ds_read_b128 v[174:177], v174 offset:3072
	s_add_u32 s18, s18, 0x40000
	s_addc_u32 s19, s19, 0
	s_mov_b32 m0, s25
	v_lshl_add_u64 v[218:219], s[18:19], 0, v[134:135]
	ds_read_b128 v[178:181], v161 offset:32768
	ds_read_b128 v[182:185], v161 offset:33792
	ds_read_b128 v[186:189], v161 offset:34816
	ds_read_b128 v[190:193], v161 offset:35840
	ds_read_b128 v[194:197], v161 offset:36864
	ds_read_b128 v[198:201], v161 offset:37888
	ds_read_b128 v[202:205], v161 offset:38912
	ds_read_b128 v[206:209], v161 offset:39936
	global_load_lds_dwordx4 v[218:219], off
	v_lshl_add_u64 v[218:219], s[18:19], 0, v[132:133]
	s_mov_b32 m0, s26
	s_nop 0
	global_load_lds_dwordx4 v[218:219], off
	s_waitcnt vmcnt(8)
	s_waitcnt lgkmcnt(0)
	s_barrier
	s_setprio 1
	s_waitcnt lgkmcnt(0)
	v_mfma_f32_16x16x32_bf16 v[126:129], v[142:145], v[178:181], v[126:129]
	v_mfma_f32_16x16x32_bf16 v[126:129], v[146:149], v[182:185], v[126:129]
	v_mfma_f32_16x16x32_bf16 v[118:121], v[150:153], v[178:181], v[118:121]
	v_mfma_f32_16x16x32_bf16 v[118:121], v[154:157], v[182:185], v[118:121]
	v_mfma_f32_16x16x32_bf16 v[110:113], v[142:145], v[186:189], v[110:113]
	v_mfma_f32_16x16x32_bf16 v[110:113], v[146:149], v[190:193], v[110:113]
	v_mfma_f32_16x16x32_bf16 v[102:105], v[150:153], v[186:189], v[102:105]
	v_mfma_f32_16x16x32_bf16 v[102:105], v[154:157], v[190:193], v[102:105]
	v_mfma_f32_16x16x32_bf16 v[94:97], v[142:145], v[194:197], v[94:97]
	v_mfma_f32_16x16x32_bf16 v[94:97], v[146:149], v[198:201], v[94:97]
	v_mfma_f32_16x16x32_bf16 v[86:89], v[150:153], v[194:197], v[86:89]
	v_mfma_f32_16x16x32_bf16 v[86:89], v[154:157], v[198:201], v[86:89]
	v_mfma_f32_16x16x32_bf16 v[78:81], v[142:145], v[202:205], v[78:81]
	v_mfma_f32_16x16x32_bf16 v[78:81], v[146:149], v[206:209], v[78:81]
	v_mfma_f32_16x16x32_bf16 v[70:73], v[150:153], v[202:205], v[70:73]
	v_mfma_f32_16x16x32_bf16 v[70:73], v[154:157], v[206:209], v[70:73]
	s_setprio 0
	s_setprio 1
	v_mfma_f32_16x16x32_bf16 v[122:125], v[162:165], v[178:181], v[122:125]
	v_mfma_f32_16x16x32_bf16 v[122:125], v[166:169], v[182:185], v[122:125]
	v_mfma_f32_16x16x32_bf16 v[114:117], v[170:173], v[178:181], v[114:117]
	v_mfma_f32_16x16x32_bf16 v[114:117], v[174:177], v[182:185], v[114:117]
	v_mfma_f32_16x16x32_bf16 v[106:109], v[162:165], v[186:189], v[106:109]
	v_mfma_f32_16x16x32_bf16 v[106:109], v[166:169], v[190:193], v[106:109]
	v_mfma_f32_16x16x32_bf16 v[98:101], v[170:173], v[186:189], v[98:101]
	v_mfma_f32_16x16x32_bf16 v[98:101], v[174:177], v[190:193], v[98:101]
	v_mfma_f32_16x16x32_bf16 v[90:93], v[162:165], v[194:197], v[90:93]
	v_mfma_f32_16x16x32_bf16 v[90:93], v[166:169], v[198:201], v[90:93]
	v_mfma_f32_16x16x32_bf16 v[82:85], v[170:173], v[194:197], v[82:85]
	v_mfma_f32_16x16x32_bf16 v[82:85], v[174:177], v[198:201], v[82:85]
	v_mfma_f32_16x16x32_bf16 v[74:77], v[162:165], v[202:205], v[74:77]
	v_mfma_f32_16x16x32_bf16 v[74:77], v[166:169], v[206:209], v[74:77]
	v_mfma_f32_16x16x32_bf16 v[66:69], v[170:173], v[202:205], v[66:69]
	v_mfma_f32_16x16x32_bf16 v[66:69], v[174:177], v[206:209], v[66:69]
	s_setprio 0
	s_barrier
	s_add_i32 s18, s38, s22
	v_lshl_add_u64 v[210:211], v[210:211], 0, s[74:75]
	s_mov_b32 m0, s18
	ds_read_b128 v[178:181], v161 offset:49152
	ds_read_b128 v[182:185], v161 offset:50176
	ds_read_b128 v[186:189], v161 offset:51200
	ds_read_b128 v[190:193], v161 offset:52224
	ds_read_b128 v[194:197], v161 offset:53248
	ds_read_b128 v[198:201], v161 offset:54272
	ds_read_b128 v[202:205], v161 offset:55296
	ds_read_b128 v[206:209], v161 offset:56320
	global_load_lds_dwordx4 v[210:211], off
	s_add_i32 m0, s18, 0x2000
	s_add_u32 s2, s2, 0x40080
	v_lshl_add_u64 v[210:211], v[212:213], 0, s[74:75]
	s_addc_u32 s3, s3, 0
	s_add_i32 s18, s39, s22
	global_load_lds_dwordx4 v[210:211], off
	v_lshl_add_u64 v[210:211], s[2:3], 0, v[0:1]
	s_mov_b32 m0, s18
	s_nop 0
	global_load_lds_dwordx4 v[210:211], off
	v_lshl_add_u64 v[210:211], s[2:3], 0, v[130:131]
	s_add_i32 m0, s18, 0x2000
	s_nop 0
	global_load_lds_dwordx4 v[210:211], off
	v_lshl_add_u64 v[210:211], v[214:215], 0, s[74:75]
	s_mov_b32 m0, s27
	s_nop 0
	global_load_lds_dwordx4 v[210:211], off
	v_lshl_add_u64 v[210:211], v[216:217], 0, s[74:75]
	s_mov_b32 m0, s28
	s_nop 0
	global_load_lds_dwordx4 v[210:211], off
	s_waitcnt vmcnt(8)
	s_waitcnt lgkmcnt(0)
	s_barrier
	s_setprio 1
	s_waitcnt lgkmcnt(0)
	v_mfma_f32_16x16x32_bf16 v[62:65], v[142:145], v[178:181], v[62:65]
	v_mfma_f32_16x16x32_bf16 v[62:65], v[146:149], v[182:185], v[62:65]
	v_mfma_f32_16x16x32_bf16 v[54:57], v[150:153], v[178:181], v[54:57]
	v_mfma_f32_16x16x32_bf16 v[54:57], v[154:157], v[182:185], v[54:57]
	v_mfma_f32_16x16x32_bf16 v[46:49], v[142:145], v[186:189], v[46:49]
	v_mfma_f32_16x16x32_bf16 v[46:49], v[146:149], v[190:193], v[46:49]
	v_mfma_f32_16x16x32_bf16 v[38:41], v[150:153], v[186:189], v[38:41]
	v_mfma_f32_16x16x32_bf16 v[38:41], v[154:157], v[190:193], v[38:41]
	v_mfma_f32_16x16x32_bf16 v[30:33], v[142:145], v[194:197], v[30:33]
	v_mfma_f32_16x16x32_bf16 v[30:33], v[146:149], v[198:201], v[30:33]
	v_mfma_f32_16x16x32_bf16 v[22:25], v[150:153], v[194:197], v[22:25]
	v_mfma_f32_16x16x32_bf16 v[22:25], v[154:157], v[198:201], v[22:25]
	v_mfma_f32_16x16x32_bf16 v[14:17], v[142:145], v[202:205], v[14:17]
	v_mfma_f32_16x16x32_bf16 v[14:17], v[146:149], v[206:209], v[14:17]
	v_mfma_f32_16x16x32_bf16 v[6:9], v[150:153], v[202:205], v[6:9]
	v_mfma_f32_16x16x32_bf16 v[6:9], v[154:157], v[206:209], v[6:9]
	s_setprio 0
	s_setprio 1
	v_mfma_f32_16x16x32_bf16 v[58:61], v[162:165], v[178:181], v[58:61]
	v_mfma_f32_16x16x32_bf16 v[58:61], v[166:169], v[182:185], v[58:61]
	v_mfma_f32_16x16x32_bf16 v[50:53], v[170:173], v[178:181], v[50:53]
	v_mfma_f32_16x16x32_bf16 v[50:53], v[174:177], v[182:185], v[50:53]
	v_mfma_f32_16x16x32_bf16 v[42:45], v[162:165], v[186:189], v[42:45]
	v_mfma_f32_16x16x32_bf16 v[42:45], v[166:169], v[190:193], v[42:45]
	v_mfma_f32_16x16x32_bf16 v[34:37], v[170:173], v[186:189], v[34:37]
	v_mfma_f32_16x16x32_bf16 v[34:37], v[174:177], v[190:193], v[34:37]
	v_mfma_f32_16x16x32_bf16 v[26:29], v[162:165], v[194:197], v[26:29]
	v_mfma_f32_16x16x32_bf16 v[26:29], v[166:169], v[198:201], v[26:29]
	v_mfma_f32_16x16x32_bf16 v[18:21], v[170:173], v[194:197], v[18:21]
	v_mfma_f32_16x16x32_bf16 v[18:21], v[174:177], v[198:201], v[18:21]
	v_mfma_f32_16x16x32_bf16 v[10:13], v[162:165], v[202:205], v[10:13]
	v_mfma_f32_16x16x32_bf16 v[10:13], v[166:169], v[206:209], v[10:13]
	v_mfma_f32_16x16x32_bf16 v[2:5], v[170:173], v[202:205], v[2:5]
	v_mfma_f32_16x16x32_bf16 v[2:5], v[174:177], v[206:209], v[2:5]
	s_setprio 0
	s_barrier
	s_add_i32 s37, s37, 2
	s_add_u32 s16, s16, 0x100
	s_addc_u32 s17, s17, 0
	s_add_u32 s33, s33, 0x100
	s_addc_u32 s36, s36, 0
	s_cmp_gt_u32 s37, 13
	s_cbranch_scc0 .LBB0_598
	s_and_b64 vcc, exec, s[6:7]
	s_cbranch_vccz .LBB0_601
	s_barrier
